# conv halo-row loads de-serialized in ssd_out and ssd_states x-conv; out_proj kscale loads batched; rstd loads hoisted
# speedup vs baseline: 1.0193x; 1.0122x over previous
.LBB0_492:
	s_andn2_b64 vcc, exec, s[10:11]
	s_cbranch_vccnz .LBB0_504
	global_load_dword v0, v[148:149], off offset:4
	global_load_dword v2, v[148:149], off offset:132
	global_load_dword v164, v[148:149], off offset:260
	global_load_dword v166, v[148:149], off offset:388
	global_load_dword v168, v[150:151], off offset:4
	global_load_dword v170, v[152:153], off offset:4
	global_load_dword v172, v[154:155], off offset:4
	global_load_dword v162, v[156:157], off offset:4
	s_cmpk_lg_i32 s44, 0x400
	s_cbranch_scc1 .Lks_wait
	global_load_dword v174, v[148:149], off
	global_load_dword v175, v[148:149], off offset:128
	global_load_dword v176, v[148:149], off offset:256
	global_load_dword v177, v[148:149], off offset:384
	global_load_dword v178, v[150:151], off
	global_load_dword v179, v[152:153], off
	global_load_dword v180, v[154:155], off
	global_load_dword v181, v[156:157], off
	s_waitcnt vmcnt(0)
	v_rcp_f32_e32 v0, v0
	v_rcp_f32_e32 v2, v2
	v_rcp_f32_e32 v164, v164
	v_rcp_f32_e32 v166, v166
	v_rcp_f32_e32 v168, v168
	v_rcp_f32_e32 v170, v170
	v_rcp_f32_e32 v172, v172
	v_rcp_f32_e32 v162, v162
	s_nop 0
	v_mul_f32_e32 v0, v0, v174
	v_mul_f32_e32 v2, v2, v175
	v_mul_f32_e32 v164, v164, v176
	v_mul_f32_e32 v166, v166, v177
	v_mul_f32_e32 v168, v168, v178
	v_mul_f32_e32 v170, v170, v179
	v_mul_f32_e32 v172, v172, v180
	v_mul_f32_e32 v162, v162, v181

.LBB0_506:
	s_cmp_eq_u32 s15, 16
	s_cselect_b64 s[10:11], -1, 0
	s_cbranch_execz .LBB0_491
	s_branch .LBB0_492
.LBB0_513:
	s_and_b64 vcc, exec, s[2:3]
	s_cbranch_vccz .LBB0_515
	s_barrier

.LBB0_567:
	s_or_b32 s12, s22, s71
	v_lshl_or_b32 v2, s12, 8, v129
	v_lshlrev_b64 v[4:5], 2, v[2:3]
	v_lshl_add_u64 v[6:7], s[54:55], 0, v[4:5]
	v_lshl_add_u64 v[8:9], s[16:17], 0, v[4:5]
	global_load_dwordx4 v[68:71], v[6:7], off
	global_load_dwordx4 v[72:75], v[8:9], off
	v_lshl_add_u64 v[6:7], s[88:89], 0, v[4:5]
	v_lshl_add_u64 v[8:9], s[90:91], 0, v[4:5]
	v_lshl_add_u64 v[4:5], s[6:7], 0, v[4:5]
	global_load_dwordx4 v[76:79], v[6:7], off
	global_load_dwordx4 v[80:83], v[8:9], off
	global_load_dwordx4 v[84:87], v[4:5], off
	v_lshlrev_b32_e32 v2, 1, v2
	v_lshl_add_u64 v[4:5], s[96:97], 0, v[2:3]
	s_and_b64 vcc, exec, s[50:51]
	v_mov_b32_e32 v104, 0
	s_cbranch_vccnz .LBB0_584
	v_add_co_u32_e32 v6, vcc, 0xffffc000, v4
	s_nop 1
	v_addc_co_u32_e32 v7, vcc, -1, v5, vcc
	global_load_dwordx2 v[210:211], v[6:7], off
	v_add_co_u32_e32 v6, vcc, 0xffffe000, v4
	s_nop 1
	v_addc_co_u32_e32 v7, vcc, -1, v5, vcc
	global_load_dwordx2 v[208:209], v[6:7], off offset:-1536
	s_and_b64 vcc, exec, s[50:51]
	v_mov_b32_e32 v105, 0
	s_cbranch_vccnz .LBB0_570

.LBB0_570:
	v_add_co_u32_e32 v6, vcc, 0x2000, v4
	s_nop 1
	v_addc_co_u32_e32 v7, vcc, 0, v5, vcc
	global_load_dwordx2 v[118:119], v[4:5], off offset:3584
	global_load_dwordx2 v[120:121], v[6:7], off offset:2048
	v_add_co_u32_e32 v6, vcc, 0x4000, v4
	s_nop 1
	v_addc_co_u32_e32 v7, vcc, 0, v5, vcc
	global_load_dwordx2 v[122:123], v[6:7], off offset:512
	v_add_co_u32_e32 v6, vcc, 0x5000, v4
	s_nop 1
	v_addc_co_u32_e32 v7, vcc, 0, v5, vcc
	global_load_dwordx2 v[148:149], v[6:7], off offset:3072
	v_add_co_u32_e32 v6, vcc, 0x7000, v4
	s_nop 1
	v_addc_co_u32_e32 v7, vcc, 0, v5, vcc
	global_load_dwordx2 v[108:109], v[6:7], off offset:1536
	v_add_co_u32_e32 v6, vcc, 0x9000, v4
	s_xor_b64 s[2:3], s[10:11], -1
	s_nop 0
	v_addc_co_u32_e32 v7, vcc, 0, v5, vcc
	global_load_dwordx2 v[110:111], v[6:7], off
	v_add_co_u32_e32 v6, vcc, s35, v4
	s_lshl_b32 s10, s12, 2
	s_nop 0
	v_addc_co_u32_e32 v7, vcc, 0, v5, vcc
	global_load_dwordx2 v[112:113], v[6:7], off offset:2560
	v_add_co_u32_e32 v6, vcc, s36, v4
	s_add_i32 s12, s68, s10
	s_nop 0
	v_addc_co_u32_e32 v7, vcc, 0, v5, vcc
	global_load_dwordx2 v[116:117], v[6:7], off offset:1024
	v_add_co_u32_e32 v6, vcc, 0xd000, v4
	s_ashr_i32 s13, s12, 31
	s_nop 0
	v_addc_co_u32_e32 v7, vcc, 0, v5, vcc
	global_load_dwordx2 v[96:97], v[6:7], off offset:3584
	v_add_co_u32_e32 v6, vcc, 0xf000, v4
	s_lshl_b64 s[12:13], s[12:13], 14
	s_nop 0
	v_addc_co_u32_e32 v7, vcc, 0, v5, vcc
	global_load_dwordx2 v[98:99], v[6:7], off offset:2048
	v_add_co_u32_e32 v6, vcc, s56, v4
	v_lshl_add_u64 v[52:53], v[140:141], 0, s[12:13]
	s_nop 0
	v_addc_co_u32_e32 v7, vcc, 0, v5, vcc
	global_load_dwordx2 v[100:101], v[6:7], off offset:512
	v_add_co_u32_e32 v6, vcc, s33, v4
	s_movk_i32 s0, 0x1000
	s_nop 0
	v_addc_co_u32_e32 v7, vcc, 0, v5, vcc
	global_load_dwordx2 v[102:103], v[6:7], off offset:3072
	v_add_co_u32_e32 v6, vcc, s65, v4
	s_nop 1
	v_addc_co_u32_e32 v7, vcc, 0, v5, vcc
	global_load_dwordx2 v[88:89], v[6:7], off offset:1536
	v_add_co_u32_e32 v6, vcc, s31, v4
	s_nop 1
	v_addc_co_u32_e32 v7, vcc, 0, v5, vcc
	global_load_dwordx2 v[90:91], v[6:7], off
	v_add_co_u32_e32 v6, vcc, s58, v4
	s_nop 1
	v_addc_co_u32_e32 v7, vcc, 0, v5, vcc
	v_add_co_u32_e32 v4, vcc, s59, v4
	s_waitcnt vmcnt(13)
	v_lshlrev_b32_e32 v158, 16, v210
	v_and_b32_e32 v154, 0xffff0000, v210
	v_lshlrev_b32_e32 v150, 16, v211
	v_and_b32_e32 v106, 0xffff0000, v211
	v_lshlrev_b32_e32 v160, 16, v208
	v_and_b32_e32 v156, 0xffff0000, v208
	v_lshlrev_b32_e32 v152, 16, v209
	v_and_b32_e32 v114, 0xffff0000, v209
	v_lshlrev_b32_e32 v164, 16, v104
	v_mov_b32_e32 v161, v164
	v_mov_b32_e32 v159, v160
	v_mov_b32_e32 v155, v156
	v_mov_b32_e32 v151, v152
	v_mov_b32_e32 v107, v114
	v_lshlrev_b32_e32 v162, 16, v118
	s_waitcnt vmcnt(12)
	v_lshlrev_b32_e32 v163, 16, v120
	v_mov_b32_e32 v165, v162
	v_pk_fma_f32 v[182:183], v[162:163], v[80:81], v[84:85] op_sel_hi:[1,0,0]
	v_mov_b32_e32 v166, v163
	v_pk_fma_f32 v[182:183], v[164:165], v[76:77], v[182:183] op_sel_hi:[1,0,1]
	s_waitcnt vmcnt(11)
	v_lshlrev_b32_e32 v167, 16, v122
	v_pk_fma_f32 v[182:183], v[160:161], v[72:73], v[182:183] op_sel_hi:[1,0,1]
	v_mov_b32_e32 v180, v167
	v_pk_fma_f32 v[158:159], v[158:159], v[68:69], v[182:183] op_sel_hi:[1,0,1]
	global_load_dwordx2 v[92:93], v[6:7], off offset:2560
	v_mul_f32_e32 v2, 0xbfb8aa3b, v158
	v_exp_f32_e32 v2, v2
	s_waitcnt vmcnt(11)
	v_lshlrev_b32_e32 v181, 16, v148
	v_addc_co_u32_e32 v5, vcc, 0, v5, vcc
	v_add_f32_e32 v2, 1.0, v2
	v_rcp_f32_e32 v160, v2
	v_mul_f32_e32 v2, 0xbfb8aa3b, v159
	v_exp_f32_e32 v2, v2
	global_load_dwordx2 v[94:95], v[4:5], off offset:1024
	v_add_co_u32_e32 v32, vcc, s0, v52
	v_add_f32_e32 v2, 1.0, v2
	v_rcp_f32_e32 v161, v2
	v_addc_co_u32_e32 v33, vcc, 0, v53, vcc
	v_add_co_u32_e32 v48, vcc, s30, v52
	v_pk_mul_f32 v[158:159], v[158:159], v[160:161]
	v_pk_fma_f32 v[160:161], v[180:181], v[80:81], v[84:85] op_sel_hi:[1,0,0]
	v_cvt_pk_bf16_f32 v158, v158, v159
	v_pk_fma_f32 v[160:161], v[166:167], v[76:77], v[160:161] op_sel_hi:[1,0,1]
	v_addc_co_u32_e32 v49, vcc, 0, v53, vcc
	v_pk_fma_f32 v[160:161], v[162:163], v[72:73], v[160:161] op_sel_hi:[1,0,1]
	s_waitcnt vmcnt(8)
	v_lshlrev_b32_e32 v183, 16, v116
	v_pk_fma_f32 v[160:161], v[164:165], v[68:69], v[160:161] op_sel_hi:[1,0,1]
	v_lshlrev_b32_e32 v165, 16, v112
	v_mul_f32_e32 v2, 0xbfb8aa3b, v160
	v_exp_f32_e32 v2, v2
	v_mov_b32_e32 v182, v165
	s_movk_i32 s0, 0x3000
	v_add_co_u32_e32 v64, vcc, s0, v52
	v_add_f32_e32 v2, 1.0, v2
	v_rcp_f32_e32 v162, v2
	v_mul_f32_e32 v2, 0xbfb8aa3b, v161
	v_exp_f32_e32 v2, v2
	v_addc_co_u32_e32 v65, vcc, 0, v53, vcc
	global_load_dwordx4 v[4:7], v[52:53], off
	global_load_dwordx4 v[8:11], v[52:53], off offset:64
	global_load_dwordx4 v[12:15], v[52:53], off offset:128
	global_load_dwordx4 v[16:19], v[52:53], off offset:192
	v_add_f32_e32 v2, 1.0, v2
	v_rcp_f32_e32 v163, v2
	global_load_dwordx4 v[20:23], v[48:49], off offset:-4096
	global_load_dwordx4 v[24:27], v[32:33], off offset:64
	global_load_dwordx4 v[28:31], v[32:33], off offset:128
	s_nop 0
	global_load_dwordx4 v[32:35], v[32:33], off offset:192
	s_nop 0
	global_load_dwordx4 v[36:39], v[48:49], off
	global_load_dwordx4 v[40:43], v[48:49], off offset:64
	global_load_dwordx4 v[44:47], v[48:49], off offset:128
	s_nop 0
	global_load_dwordx4 v[48:51], v[48:49], off offset:192
	s_nop 0
	global_load_dwordx4 v[52:55], v[64:65], off
	global_load_dwordx4 v[56:59], v[64:65], off offset:64
	global_load_dwordx4 v[60:63], v[64:65], off offset:128
	s_nop 0
	global_load_dwordx4 v[64:67], v[64:65], off offset:192
	s_add_i32 s13, s10, s69
	v_pk_mul_f32 v[160:161], v[160:161], v[162:163]
	v_lshlrev_b32_e32 v163, 16, v110
	v_lshlrev_b32_e32 v162, 16, v108
	v_cvt_pk_bf16_f32 v159, v160, v161
	v_pk_fma_f32 v[160:161], v[162:163], v[80:81], v[84:85] op_sel_hi:[1,0,0]
	v_pk_mov_b32 v[184:185], v[180:181], v[162:163] op_sel:[1,0]
	v_mov_b32_e32 v164, v163
	v_pk_fma_f32 v[160:161], v[184:185], v[76:77], v[160:161] op_sel_hi:[1,0,1]
	s_add_i32 s10, s13, s4
	v_pk_fma_f32 v[160:161], v[180:181], v[72:73], v[160:161] op_sel_hi:[1,0,1]
	s_ashr_i32 s11, s10, 31
	v_pk_fma_f32 v[160:161], v[166:167], v[68:69], v[160:161] op_sel_hi:[1,0,1]
	s_lshl_b64 s[10:11], s[10:11], 2
	v_mul_f32_e32 v2, 0xbfb8aa3b, v160
	v_exp_f32_e32 v2, v2
	s_add_u32 s10, s86, s10
	s_addc_u32 s11, s87, s11
	s_lshl_b32 s14, s13, 9
	v_add_f32_e32 v2, 1.0, v2
	v_rcp_f32_e32 v166, v2
	v_mul_f32_e32 v2, 0xbfb8aa3b, v161
	v_exp_f32_e32 v2, v2
	s_mov_b32 s66, 0
	s_add_i32 s12, s14, 0
	v_add_f32_e32 v2, 1.0, v2
	v_rcp_f32_e32 v167, v2
	s_nop 0
	v_pk_mul_f32 v[160:161], v[160:161], v[166:167]
	v_pk_fma_f32 v[166:167], v[182:183], v[80:81], v[84:85] op_sel_hi:[1,0,0]
	v_cvt_pk_bf16_f32 v160, v160, v161
	v_pk_fma_f32 v[166:167], v[164:165], v[76:77], v[166:167] op_sel_hi:[1,0,1]
	s_nop 0
	v_pk_fma_f32 v[162:163], v[162:163], v[72:73], v[166:167] op_sel_hi:[1,0,1]
	s_nop 0
	v_pk_fma_f32 v[162:163], v[184:185], v[68:69], v[162:163] op_sel_hi:[1,0,1]
	s_nop 0
	v_mul_f32_e32 v2, 0xbfb8aa3b, v162
	v_exp_f32_e32 v2, v2
	s_nop 0
	v_add_f32_e32 v2, 1.0, v2
	v_rcp_f32_e32 v166, v2
	v_mul_f32_e32 v2, 0xbfb8aa3b, v163
	v_exp_f32_e32 v2, v2
	s_nop 0
	v_add_f32_e32 v2, 1.0, v2
	v_rcp_f32_e32 v167, v2
	s_nop 0
	v_pk_mul_f32 v[162:163], v[162:163], v[166:167]
	s_nop 0
	v_cvt_pk_bf16_f32 v161, v162, v163
	ds_write_b128 v178, v[158:161]
	s_waitcnt vmcnt(22)
	v_lshlrev_b32_e32 v161, 16, v98
	v_lshlrev_b32_e32 v160, 16, v96
	v_pk_fma_f32 v[158:159], v[160:161], v[80:81], v[84:85] op_sel_hi:[1,0,0]
	v_pk_mov_b32 v[180:181], v[182:183], v[160:161] op_sel:[1,0]
	s_waitcnt vmcnt(21)
	v_lshlrev_b32_e32 v163, 16, v100
	v_pk_fma_f32 v[158:159], v[180:181], v[76:77], v[158:159] op_sel_hi:[1,0,1]
	s_waitcnt vmcnt(20)
	v_lshlrev_b32_e32 v167, 16, v102
	v_pk_fma_f32 v[158:159], v[182:183], v[72:73], v[158:159] op_sel_hi:[1,0,1]
	v_mov_b32_e32 v166, v163
	v_pk_fma_f32 v[158:159], v[164:165], v[68:69], v[158:159] op_sel_hi:[1,0,1]
	v_mov_b32_e32 v162, v161
	v_mul_f32_e32 v2, 0xbfb8aa3b, v158
	v_exp_f32_e32 v2, v2
	s_waitcnt vmcnt(16)
	v_lshlrev_b32_e32 v183, 16, v94
	v_add_f32_e32 v2, 1.0, v2
	v_rcp_f32_e32 v164, v2
	v_mul_f32_e32 v2, 0xbfb8aa3b, v159
	v_exp_f32_e32 v2, v2
	s_nop 0
	v_add_f32_e32 v2, 1.0, v2
	v_rcp_f32_e32 v165, v2
	s_nop 0
	v_pk_mul_f32 v[158:159], v[158:159], v[164:165]
	v_pk_fma_f32 v[164:165], v[166:167], v[80:81], v[84:85] op_sel_hi:[1,0,0]
	v_cvt_pk_bf16_f32 v158, v158, v159
	v_pk_fma_f32 v[164:165], v[162:163], v[76:77], v[164:165] op_sel_hi:[1,0,1]
	s_nop 0
	v_pk_fma_f32 v[160:161], v[160:161], v[72:73], v[164:165] op_sel_hi:[1,0,1]
	s_nop 0
	v_pk_fma_f32 v[160:161], v[180:181], v[68:69], v[160:161] op_sel_hi:[1,0,1]
	v_lshlrev_b32_e32 v181, 16, v92
	v_mul_f32_e32 v2, 0xbfb8aa3b, v160
	v_exp_f32_e32 v2, v2
	v_mov_b32_e32 v182, v181
	v_add_f32_e32 v2, 1.0, v2
	v_rcp_f32_e32 v164, v2
	v_mul_f32_e32 v2, 0xbfb8aa3b, v161
	v_exp_f32_e32 v2, v2
	s_nop 0
	v_add_f32_e32 v2, 1.0, v2
	v_rcp_f32_e32 v165, v2
	s_nop 0
	v_pk_mul_f32 v[160:161], v[160:161], v[164:165]
	v_lshlrev_b32_e32 v164, 16, v88
	v_lshlrev_b32_e32 v165, 16, v90
	v_cvt_pk_bf16_f32 v159, v160, v161
	v_pk_fma_f32 v[160:161], v[164:165], v[80:81], v[84:85] op_sel_hi:[1,0,0]
	v_pk_mov_b32 v[184:185], v[166:167], v[164:165] op_sel:[1,0]
	v_mov_b32_e32 v180, v165
	v_pk_fma_f32 v[160:161], v[184:185], v[76:77], v[160:161] op_sel_hi:[1,0,1]
	s_nop 0
	v_pk_fma_f32 v[160:161], v[166:167], v[72:73], v[160:161] op_sel_hi:[1,0,1]
	s_nop 0
	v_pk_fma_f32 v[160:161], v[162:163], v[68:69], v[160:161] op_sel_hi:[1,0,1]
	s_nop 0
	v_mul_f32_e32 v2, 0xbfb8aa3b, v160
	v_exp_f32_e32 v2, v2
	s_nop 0
	v_add_f32_e32 v2, 1.0, v2
	v_rcp_f32_e32 v162, v2
	v_mul_f32_e32 v2, 0xbfb8aa3b, v161
	v_exp_f32_e32 v2, v2
	s_nop 0
	v_add_f32_e32 v2, 1.0, v2
	v_rcp_f32_e32 v163, v2
	s_nop 0
	v_pk_mul_f32 v[160:161], v[160:161], v[162:163]
	v_pk_fma_f32 v[162:163], v[182:183], v[80:81], v[84:85] op_sel_hi:[1,0,0]
	v_cvt_pk_bf16_f32 v160, v160, v161
	v_pk_fma_f32 v[162:163], v[180:181], v[76:77], v[162:163] op_sel_hi:[1,0,1]
	s_nop 0
	v_pk_fma_f32 v[162:163], v[164:165], v[72:73], v[162:163] op_sel_hi:[1,0,1]
	s_nop 0
	v_pk_fma_f32 v[162:163], v[184:185], v[68:69], v[162:163] op_sel_hi:[1,0,1]
	s_nop 0
	v_mul_f32_e32 v2, 0xbfb8aa3b, v162
	v_exp_f32_e32 v2, v2
	s_nop 0
	v_add_f32_e32 v2, 1.0, v2
	v_rcp_f32_e32 v164, v2
	v_mul_f32_e32 v2, 0xbfb8aa3b, v163
	v_exp_f32_e32 v2, v2
	s_nop 0
	v_add_f32_e32 v2, 1.0, v2
	v_rcp_f32_e32 v165, v2
	s_nop 0
	v_pk_mul_f32 v[162:163], v[162:163], v[164:165]
	s_nop 0
	v_cvt_pk_bf16_f32 v161, v162, v163
	ds_write_b128 v178, v[158:161] offset:16
	v_and_b32_e32 v159, 0xffff0000, v118
	v_and_b32_e32 v161, 0xffff0000, v120
	v_mov_b32_e32 v160, v159
	v_and_b32_e32 v158, 0xffff0000, v104
	v_pk_fma_f32 v[166:167], v[160:161], v[80:81], v[84:85] op_sel:[0,1,1]
	v_mov_b32_e32 v157, v158
	v_pk_fma_f32 v[166:167], v[158:159], v[76:77], v[166:167] op_sel:[0,1,0]
	v_and_b32_e32 v163, 0xffff0000, v122
	v_pk_fma_f32 v[166:167], v[156:157], v[72:73], v[166:167] op_sel:[0,1,0]
	v_and_b32_e32 v165, 0xffff0000, v148
	v_pk_fma_f32 v[154:155], v[154:155], v[68:69], v[166:167] op_sel:[0,1,0]
	v_mov_b32_e32 v164, v163
	v_mul_f32_e32 v2, 0xbfb8aa3b, v154
	v_exp_f32_e32 v2, v2
	v_mov_b32_e32 v162, v161
	v_add_f32_e32 v2, 1.0, v2
	v_rcp_f32_e32 v156, v2
	v_mul_f32_e32 v2, 0xbfb8aa3b, v155
	v_exp_f32_e32 v2, v2
	s_nop 0
	v_add_f32_e32 v2, 1.0, v2
	v_rcp_f32_e32 v157, v2
	s_nop 0
	v_pk_mul_f32 v[154:155], v[154:155], v[156:157]
	v_pk_fma_f32 v[156:157], v[164:165], v[80:81], v[84:85] op_sel:[0,1,1]
	v_cvt_pk_bf16_f32 v154, v154, v155
	v_pk_fma_f32 v[156:157], v[162:163], v[76:77], v[156:157] op_sel:[0,1,0]
	s_nop 0
	v_pk_fma_f32 v[156:157], v[160:161], v[72:73], v[156:157] op_sel:[0,1,0]
	v_and_b32_e32 v161, 0xffff0000, v116
	v_pk_fma_f32 v[156:157], v[158:159], v[68:69], v[156:157] op_sel:[0,1,0]
	s_nop 0
	v_mul_f32_e32 v2, 0xbfb8aa3b, v156
	v_exp_f32_e32 v2, v2
	s_nop 0
	v_add_f32_e32 v2, 1.0, v2
	v_rcp_f32_e32 v158, v2
	v_mul_f32_e32 v2, 0xbfb8aa3b, v157
	v_exp_f32_e32 v2, v2
	s_nop 0
	v_add_f32_e32 v2, 1.0, v2
	v_rcp_f32_e32 v159, v2
	s_nop 0
	v_pk_mul_f32 v[156:157], v[156:157], v[158:159]
	s_nop 0
	v_cvt_pk_bf16_f32 v155, v156, v157
	v_and_b32_e32 v157, 0xffff0000, v110
	v_and_b32_e32 v156, 0xffff0000, v108
	v_pk_fma_f32 v[166:167], v[156:157], v[80:81], v[84:85] op_sel:[0,1,1]
	v_pk_mov_b32 v[180:181], v[164:165], v[156:157] op_sel:[1,0]
	v_and_b32_e32 v159, 0xffff0000, v112
	v_pk_fma_f32 v[166:167], v[180:181], v[76:77], v[166:167] op_sel:[0,1,0]
	v_mov_b32_e32 v160, v159
	v_pk_fma_f32 v[164:165], v[164:165], v[72:73], v[166:167] op_sel:[0,1,0]
	v_mov_b32_e32 v158, v157
	v_pk_fma_f32 v[162:163], v[162:163], v[68:69], v[164:165] op_sel:[0,1,0]
	s_nop 0
	v_mul_f32_e32 v2, 0xbfb8aa3b, v162
	v_exp_f32_e32 v2, v2
	s_nop 0
	v_add_f32_e32 v2, 1.0, v2
	v_rcp_f32_e32 v164, v2
	v_mul_f32_e32 v2, 0xbfb8aa3b, v163
	v_exp_f32_e32 v2, v2
	s_nop 0
	v_add_f32_e32 v2, 1.0, v2
	v_rcp_f32_e32 v165, v2
	s_nop 0
	v_pk_mul_f32 v[162:163], v[162:163], v[164:165]
	v_pk_fma_f32 v[164:165], v[160:161], v[80:81], v[84:85] op_sel:[0,1,1]
	v_cvt_pk_bf16_f32 v162, v162, v163
	v_pk_fma_f32 v[164:165], v[158:159], v[76:77], v[164:165] op_sel:[0,1,0]
	s_nop 0
	v_pk_fma_f32 v[156:157], v[156:157], v[72:73], v[164:165] op_sel:[0,1,0]
	s_nop 0
	v_pk_fma_f32 v[156:157], v[180:181], v[68:69], v[156:157] op_sel:[0,1,0]
	s_nop 0
	v_mul_f32_e32 v2, 0xbfb8aa3b, v156
	v_exp_f32_e32 v2, v2
	s_nop 0
	v_add_f32_e32 v2, 1.0, v2
	v_rcp_f32_e32 v164, v2
	v_mul_f32_e32 v2, 0xbfb8aa3b, v157
	v_exp_f32_e32 v2, v2
	s_nop 0
	v_add_f32_e32 v2, 1.0, v2
	v_rcp_f32_e32 v165, v2
	s_nop 0
	v_pk_mul_f32 v[156:157], v[156:157], v[164:165]
	s_nop 0
	v_cvt_pk_bf16_f32 v163, v156, v157
	ds_write2_b64 v178, v[154:155], v[162:163] offset0:33 offset1:34
	v_and_b32_e32 v155, 0xffff0000, v98
	v_and_b32_e32 v154, 0xffff0000, v96
	v_pk_fma_f32 v[164:165], v[154:155], v[80:81], v[84:85] op_sel:[0,1,1]
	v_pk_mov_b32 v[166:167], v[160:161], v[154:155] op_sel:[1,0]
	v_and_b32_e32 v157, 0xffff0000, v100
	v_pk_fma_f32 v[164:165], v[166:167], v[76:77], v[164:165] op_sel:[0,1,0]
	v_and_b32_e32 v163, 0xffff0000, v102
	v_pk_fma_f32 v[160:161], v[160:161], v[72:73], v[164:165] op_sel:[0,1,0]
	v_mov_b32_e32 v162, v157
	v_pk_fma_f32 v[158:159], v[158:159], v[68:69], v[160:161] op_sel:[0,1,0]
	v_mov_b32_e32 v156, v155
	v_mul_f32_e32 v2, 0xbfb8aa3b, v158
	v_exp_f32_e32 v2, v2
	v_and_b32_e32 v165, 0xffff0000, v94
	v_add_f32_e32 v2, 1.0, v2
	v_rcp_f32_e32 v160, v2
	v_mul_f32_e32 v2, 0xbfb8aa3b, v159
	v_exp_f32_e32 v2, v2
	s_nop 0
	v_add_f32_e32 v2, 1.0, v2
	v_rcp_f32_e32 v161, v2
	s_nop 0
	v_pk_mul_f32 v[158:159], v[158:159], v[160:161]
	v_pk_fma_f32 v[160:161], v[162:163], v[80:81], v[84:85] op_sel:[0,1,1]
	v_cvt_pk_bf16_f32 v158, v158, v159
	v_pk_fma_f32 v[160:161], v[156:157], v[76:77], v[160:161] op_sel:[0,1,0]
	s_nop 0
	v_pk_fma_f32 v[154:155], v[154:155], v[72:73], v[160:161] op_sel:[0,1,0]
	s_nop 0
	v_pk_fma_f32 v[154:155], v[166:167], v[68:69], v[154:155] op_sel:[0,1,0]
	s_nop 0
	v_mul_f32_e32 v2, 0xbfb8aa3b, v154
	v_exp_f32_e32 v2, v2
	s_nop 0
	v_add_f32_e32 v2, 1.0, v2
	v_rcp_f32_e32 v160, v2
	v_mul_f32_e32 v2, 0xbfb8aa3b, v155
	v_exp_f32_e32 v2, v2
	s_nop 0
	v_add_f32_e32 v2, 1.0, v2
	v_rcp_f32_e32 v161, v2
	s_nop 0
	v_pk_mul_f32 v[154:155], v[154:155], v[160:161]
	s_nop 0
	v_cvt_pk_bf16_f32 v159, v154, v155
	v_and_b32_e32 v155, 0xffff0000, v90
	v_and_b32_e32 v154, 0xffff0000, v88
	v_pk_fma_f32 v[166:167], v[154:155], v[80:81], v[84:85] op_sel:[0,1,1]
	v_pk_mov_b32 v[180:181], v[162:163], v[154:155] op_sel:[1,0]
	v_and_b32_e32 v161, 0xffff0000, v92
	v_pk_fma_f32 v[166:167], v[180:181], v[76:77], v[166:167] op_sel:[0,1,0]
	v_mov_b32_e32 v164, v161
	v_pk_fma_f32 v[162:163], v[162:163], v[72:73], v[166:167] op_sel:[0,1,0]
	v_mov_b32_e32 v160, v155
	v_pk_fma_f32 v[156:157], v[156:157], v[68:69], v[162:163] op_sel:[0,1,0]
	v_pk_fma_f32 v[80:81], v[164:165], v[80:81], v[84:85] op_sel:[0,1,1]
	v_mul_f32_e32 v2, 0xbfb8aa3b, v156
	v_exp_f32_e32 v2, v2
	v_pk_fma_f32 v[76:77], v[160:161], v[76:77], v[80:81] op_sel:[0,1,0]
	v_lshlrev_b32_e32 v81, 16, v149
	v_pk_fma_f32 v[72:73], v[154:155], v[72:73], v[76:77] op_sel:[0,1,0]
	v_add_f32_e32 v2, 1.0, v2
	v_rcp_f32_e32 v162, v2
	v_mul_f32_e32 v2, 0xbfb8aa3b, v157
	v_exp_f32_e32 v2, v2
	v_pk_fma_f32 v[68:69], v[180:181], v[68:69], v[72:73] op_sel:[0,1,0]
	v_lshlrev_b32_e32 v77, 16, v123
	v_mov_b32_e32 v80, v77
	v_add_f32_e32 v2, 1.0, v2
	v_rcp_f32_e32 v163, v2
	v_mul_f32_e32 v2, 0xbfb8aa3b, v68
	v_exp_f32_e32 v2, v2
	v_or_b32_e32 v180, s14, v126
	v_pk_mul_f32 v[156:157], v[156:157], v[162:163]
	v_add_f32_e32 v2, 1.0, v2
	v_rcp_f32_e32 v72, v2
	v_mul_f32_e32 v2, 0xbfb8aa3b, v69
	v_exp_f32_e32 v2, v2
	v_cvt_pk_bf16_f32 v156, v156, v157
	v_add_f32_e32 v2, 1.0, v2
	v_rcp_f32_e32 v73, v2
	s_nop 0
	v_pk_mul_f32 v[68:69], v[68:69], v[72:73]
	s_nop 0
	v_cvt_pk_bf16_f32 v157, v68, v69
	v_lshlrev_b32_e32 v68, 16, v119
	v_lshlrev_b32_e32 v69, 16, v121
	v_lshlrev_b32_e32 v72, 16, v105
	v_mov_b32_e32 v73, v68
	v_pk_fma_f32 v[84:85], v[68:69], v[82:83], v[86:87] op_sel_hi:[1,0,0]
	v_mov_b32_e32 v153, v72
	v_pk_fma_f32 v[84:85], v[72:73], v[78:79], v[84:85] op_sel_hi:[1,0,1]
	v_mov_b32_e32 v76, v69
	v_pk_fma_f32 v[84:85], v[152:153], v[74:75], v[84:85] op_sel_hi:[1,0,1]
	ds_write2_b64 v178, v[158:159], v[156:157] offset0:35 offset1:36
	v_pk_fma_f32 v[84:85], v[150:151], v[70:71], v[84:85] op_sel_hi:[1,0,1]
	s_nop 0
	v_mul_f32_e32 v2, 0xbfb8aa3b, v84
	v_exp_f32_e32 v2, v2
	s_nop 0
	v_add_f32_e32 v2, 1.0, v2
	v_rcp_f32_e32 v150, v2
	v_mul_f32_e32 v2, 0xbfb8aa3b, v85
	v_exp_f32_e32 v2, v2
	s_nop 0
	v_add_f32_e32 v2, 1.0, v2
	v_rcp_f32_e32 v151, v2
	s_nop 0
	v_pk_mul_f32 v[84:85], v[84:85], v[150:151]
	s_nop 0
	v_cvt_pk_bf16_f32 v150, v84, v85
	v_pk_fma_f32 v[84:85], v[80:81], v[82:83], v[86:87] op_sel_hi:[1,0,0]
	s_nop 0
	v_pk_fma_f32 v[84:85], v[76:77], v[78:79], v[84:85] op_sel_hi:[1,0,1]
	s_nop 0
	v_pk_fma_f32 v[68:69], v[68:69], v[74:75], v[84:85] op_sel_hi:[1,0,1]
	v_lshlrev_b32_e32 v85, 16, v117
	v_pk_fma_f32 v[68:69], v[72:73], v[70:71], v[68:69] op_sel_hi:[1,0,1]
	s_nop 0
	v_mul_f32_e32 v2, 0xbfb8aa3b, v68
	v_exp_f32_e32 v2, v2
	s_nop 0
	v_add_f32_e32 v2, 1.0, v2
	v_rcp_f32_e32 v72, v2
	v_mul_f32_e32 v2, 0xbfb8aa3b, v69
	v_exp_f32_e32 v2, v2
	s_nop 0
	v_add_f32_e32 v2, 1.0, v2
	v_rcp_f32_e32 v73, v2
	s_nop 0
	v_pk_mul_f32 v[68:69], v[68:69], v[72:73]
	s_nop 0
	v_cvt_pk_bf16_f32 v151, v68, v69
	v_lshlrev_b32_e32 v69, 16, v111
	v_lshlrev_b32_e32 v68, 16, v109
	v_pk_fma_f32 v[152:153], v[68:69], v[82:83], v[86:87] op_sel_hi:[1,0,0]
	v_pk_mov_b32 v[154:155], v[80:81], v[68:69] op_sel:[1,0]
	v_lshlrev_b32_e32 v73, 16, v113
	v_pk_fma_f32 v[152:153], v[154:155], v[78:79], v[152:153] op_sel_hi:[1,0,1]
	v_mov_b32_e32 v84, v73
	v_pk_fma_f32 v[80:81], v[80:81], v[74:75], v[152:153] op_sel_hi:[1,0,1]
	v_mov_b32_e32 v72, v69
	v_pk_fma_f32 v[76:77], v[76:77], v[70:71], v[80:81] op_sel_hi:[1,0,1]
	s_nop 0
	v_mul_f32_e32 v2, 0xbfb8aa3b, v76
	v_exp_f32_e32 v2, v2
	s_nop 0
	v_add_f32_e32 v2, 1.0, v2
	v_rcp_f32_e32 v80, v2
	v_mul_f32_e32 v2, 0xbfb8aa3b, v77
	v_exp_f32_e32 v2, v2
	s_nop 0
	v_add_f32_e32 v2, 1.0, v2
	v_rcp_f32_e32 v81, v2
	s_nop 0
	v_pk_mul_f32 v[76:77], v[76:77], v[80:81]
	s_nop 0
	v_cvt_pk_bf16_f32 v152, v76, v77
	v_pk_fma_f32 v[76:77], v[84:85], v[82:83], v[86:87] op_sel_hi:[1,0,0]
	v_lshlrev_b32_e32 v81, 16, v103
	v_pk_fma_f32 v[76:77], v[72:73], v[78:79], v[76:77] op_sel_hi:[1,0,1]
	s_nop 0
	v_pk_fma_f32 v[68:69], v[68:69], v[74:75], v[76:77] op_sel_hi:[1,0,1]
	s_nop 0
	v_pk_fma_f32 v[68:69], v[154:155], v[70:71], v[68:69] op_sel_hi:[1,0,1]
	s_nop 0
	v_mul_f32_e32 v2, 0xbfb8aa3b, v68
	v_exp_f32_e32 v2, v2
	s_nop 0
	v_add_f32_e32 v2, 1.0, v2
	v_rcp_f32_e32 v76, v2
	v_mul_f32_e32 v2, 0xbfb8aa3b, v69
	v_exp_f32_e32 v2, v2
	s_nop 0
	v_add_f32_e32 v2, 1.0, v2
	v_rcp_f32_e32 v77, v2
	s_nop 0
	v_pk_mul_f32 v[68:69], v[68:69], v[76:77]
	s_nop 0
	v_cvt_pk_bf16_f32 v153, v68, v69
	v_lshlrev_b32_e32 v69, 16, v99
	v_lshlrev_b32_e32 v68, 16, v97
	ds_write_b128 v178, v[150:153] offset:528
	v_pk_fma_f32 v[150:151], v[68:69], v[82:83], v[86:87] op_sel_hi:[1,0,0]
	v_pk_mov_b32 v[152:153], v[84:85], v[68:69] op_sel:[1,0]
	v_lshlrev_b32_e32 v77, 16, v101
	v_pk_fma_f32 v[150:151], v[152:153], v[78:79], v[150:151] op_sel_hi:[1,0,1]
	v_mov_b32_e32 v80, v77
	v_pk_fma_f32 v[84:85], v[84:85], v[74:75], v[150:151] op_sel_hi:[1,0,1]
	v_mov_b32_e32 v76, v69
	v_pk_fma_f32 v[72:73], v[72:73], v[70:71], v[84:85] op_sel_hi:[1,0,1]
	s_nop 0
	v_mul_f32_e32 v2, 0xbfb8aa3b, v72
	v_exp_f32_e32 v2, v2
	s_nop 0
	v_add_f32_e32 v2, 1.0, v2
	v_rcp_f32_e32 v84, v2
	v_mul_f32_e32 v2, 0xbfb8aa3b, v73
	v_exp_f32_e32 v2, v2
	s_nop 0
	v_add_f32_e32 v2, 1.0, v2
	v_rcp_f32_e32 v85, v2
	s_nop 0
	v_pk_mul_f32 v[72:73], v[72:73], v[84:85]
	s_nop 0
	v_cvt_pk_bf16_f32 v150, v72, v73
	v_pk_fma_f32 v[72:73], v[80:81], v[82:83], v[86:87] op_sel_hi:[1,0,0]
	v_lshlrev_b32_e32 v85, 16, v95
	v_pk_fma_f32 v[72:73], v[76:77], v[78:79], v[72:73] op_sel_hi:[1,0,1]
	s_nop 0
	v_pk_fma_f32 v[68:69], v[68:69], v[74:75], v[72:73] op_sel_hi:[1,0,1]
	s_nop 0
	v_pk_fma_f32 v[68:69], v[152:153], v[70:71], v[68:69] op_sel_hi:[1,0,1]
	s_nop 0
	v_mul_f32_e32 v2, 0xbfb8aa3b, v68
	v_exp_f32_e32 v2, v2
	s_nop 0
	v_add_f32_e32 v2, 1.0, v2
	v_rcp_f32_e32 v72, v2
	v_mul_f32_e32 v2, 0xbfb8aa3b, v69
	v_exp_f32_e32 v2, v2
	s_nop 0
	v_add_f32_e32 v2, 1.0, v2
	v_rcp_f32_e32 v73, v2
	s_nop 0
	v_pk_mul_f32 v[68:69], v[68:69], v[72:73]
	s_nop 0
	v_cvt_pk_bf16_f32 v151, v68, v69
	v_lshlrev_b32_e32 v68, 16, v89
	v_lshlrev_b32_e32 v69, 16, v91
	v_pk_fma_f32 v[152:153], v[68:69], v[82:83], v[86:87] op_sel_hi:[1,0,0]
	v_pk_mov_b32 v[154:155], v[80:81], v[68:69] op_sel:[1,0]
	v_lshlrev_b32_e32 v73, 16, v93
	v_pk_fma_f32 v[152:153], v[154:155], v[78:79], v[152:153] op_sel_hi:[1,0,1]
	v_mov_b32_e32 v84, v73
	v_pk_fma_f32 v[80:81], v[80:81], v[74:75], v[152:153] op_sel_hi:[1,0,1]
	v_mov_b32_e32 v72, v69
	v_pk_fma_f32 v[76:77], v[76:77], v[70:71], v[80:81] op_sel_hi:[1,0,1]
	s_nop 0
	v_mul_f32_e32 v2, 0xbfb8aa3b, v76
	v_exp_f32_e32 v2, v2
	s_nop 0
	v_add_f32_e32 v2, 1.0, v2
	v_rcp_f32_e32 v80, v2
	v_mul_f32_e32 v2, 0xbfb8aa3b, v77
	v_exp_f32_e32 v2, v2
	s_nop 0
	v_add_f32_e32 v2, 1.0, v2
	v_rcp_f32_e32 v81, v2
	s_nop 0
	v_pk_mul_f32 v[76:77], v[76:77], v[80:81]
	s_nop 0
	v_cvt_pk_bf16_f32 v152, v76, v77
	v_pk_fma_f32 v[76:77], v[84:85], v[82:83], v[86:87] op_sel_hi:[1,0,0]
	v_and_b32_e32 v81, 0xffff0000, v121
	v_pk_fma_f32 v[72:73], v[72:73], v[78:79], v[76:77] op_sel_hi:[1,0,1]
	v_and_b32_e32 v77, 0xffff0000, v119
	v_pk_fma_f32 v[68:69], v[68:69], v[74:75], v[72:73] op_sel_hi:[1,0,1]
	v_mov_b32_e32 v80, v77
	v_pk_fma_f32 v[68:69], v[154:155], v[70:71], v[68:69] op_sel_hi:[1,0,1]
	v_and_b32_e32 v76, 0xffff0000, v105
	v_mul_f32_e32 v2, 0xbfb8aa3b, v68
	v_exp_f32_e32 v2, v2
	v_mov_b32_e32 v70, v79
	v_mov_b32_e32 v115, v76
	v_mov_b32_e32 v74, v71
	v_add_f32_e32 v2, 1.0, v2
	v_rcp_f32_e32 v72, v2
	v_mul_f32_e32 v2, 0xbfb8aa3b, v69
	v_exp_f32_e32 v2, v2
	v_and_b32_e32 v85, 0xffff0000, v123
	v_and_b32_e32 v105, 0xffff0000, v149
	v_mov_b32_e32 v104, v85
	v_add_f32_e32 v2, 1.0, v2
	v_rcp_f32_e32 v73, v2
	v_mov_b32_e32 v2, v83
	v_mov_b32_e32 v84, v81
	v_pk_mul_f32 v[68:69], v[68:69], v[72:73]
	s_nop 0
	v_cvt_pk_bf16_f32 v153, v68, v69
	v_mov_b32_e32 v68, v87
	v_pk_fma_f32 v[72:73], v[80:81], v[2:3], v[68:69] op_sel_hi:[1,0,0]
	ds_write_b128 v178, v[150:153] offset:544
	v_pk_fma_f32 v[78:79], v[76:77], v[70:71], v[72:73] op_sel_hi:[1,0,1]
	v_mov_b32_e32 v72, v75
	v_pk_fma_f32 v[78:79], v[114:115], v[72:73], v[78:79] op_sel_hi:[1,0,1]
	s_nop 0
	v_pk_fma_f32 v[78:79], v[106:107], v[74:75], v[78:79] op_sel_hi:[1,0,1]
	s_nop 0
	v_mul_f32_e32 v69, 0xbfb8aa3b, v78
	v_exp_f32_e32 v69, v69
	s_nop 0
	v_add_f32_e32 v69, 1.0, v69
	v_rcp_f32_e32 v82, v69
	v_mul_f32_e32 v69, 0xbfb8aa3b, v79
	v_exp_f32_e32 v69, v69
	s_nop 0
	v_add_f32_e32 v69, 1.0, v69
	v_rcp_f32_e32 v83, v69
	s_nop 0
	v_pk_mul_f32 v[78:79], v[78:79], v[82:83]
	v_pk_fma_f32 v[82:83], v[104:105], v[2:3], v[68:69] op_sel_hi:[1,0,0]
	v_cvt_pk_bf16_f32 v78, v78, v79
	v_pk_fma_f32 v[82:83], v[84:85], v[70:71], v[82:83] op_sel_hi:[1,0,1]
	s_nop 0
	v_pk_fma_f32 v[80:81], v[80:81], v[72:73], v[82:83] op_sel_hi:[1,0,1]
	v_and_b32_e32 v83, 0xffff0000, v117
	v_pk_fma_f32 v[76:77], v[76:77], v[74:75], v[80:81] op_sel_hi:[1,0,1]
	s_nop 0
	v_mul_f32_e32 v69, 0xbfb8aa3b, v76
	v_exp_f32_e32 v69, v69
	s_nop 0
	v_add_f32_e32 v69, 1.0, v69
	v_rcp_f32_e32 v80, v69
	v_mul_f32_e32 v69, 0xbfb8aa3b, v77
	v_exp_f32_e32 v69, v69
	s_nop 0
	v_add_f32_e32 v69, 1.0, v69
	v_rcp_f32_e32 v81, v69
	s_nop 0
	v_pk_mul_f32 v[76:77], v[76:77], v[80:81]
	s_nop 0
	v_cvt_pk_bf16_f32 v79, v76, v77
	v_and_b32_e32 v77, 0xffff0000, v111
	v_and_b32_e32 v76, 0xffff0000, v109
	v_pk_fma_f32 v[86:87], v[76:77], v[2:3], v[68:69] op_sel_hi:[1,0,0]
	v_pk_mov_b32 v[106:107], v[104:105], v[76:77] op_sel:[1,0]
	v_and_b32_e32 v81, 0xffff0000, v113
	v_pk_fma_f32 v[86:87], v[106:107], v[70:71], v[86:87] op_sel_hi:[1,0,1]
	v_mov_b32_e32 v82, v81
	v_pk_fma_f32 v[86:87], v[104:105], v[72:73], v[86:87] op_sel_hi:[1,0,1]
	v_mov_b32_e32 v80, v77
	v_pk_fma_f32 v[84:85], v[84:85], v[74:75], v[86:87] op_sel_hi:[1,0,1]
	s_nop 0
	v_mul_f32_e32 v69, 0xbfb8aa3b, v84
	v_exp_f32_e32 v69, v69
	s_nop 0
	v_add_f32_e32 v69, 1.0, v69
	v_rcp_f32_e32 v86, v69
	v_mul_f32_e32 v69, 0xbfb8aa3b, v85
	v_exp_f32_e32 v69, v69
	s_nop 0
	v_add_f32_e32 v69, 1.0, v69
	v_rcp_f32_e32 v87, v69
	s_nop 0
	v_pk_mul_f32 v[84:85], v[84:85], v[86:87]
	v_pk_fma_f32 v[86:87], v[82:83], v[2:3], v[68:69] op_sel_hi:[1,0,0]
	v_cvt_pk_bf16_f32 v84, v84, v85
	v_pk_fma_f32 v[86:87], v[80:81], v[70:71], v[86:87] op_sel_hi:[1,0,1]
	s_nop 0
	v_pk_fma_f32 v[76:77], v[76:77], v[72:73], v[86:87] op_sel_hi:[1,0,1]
	s_nop 0
	v_pk_fma_f32 v[76:77], v[106:107], v[74:75], v[76:77] op_sel_hi:[1,0,1]
	s_nop 0
	v_mul_f32_e32 v69, 0xbfb8aa3b, v76
	v_exp_f32_e32 v69, v69
	s_nop 0
	v_add_f32_e32 v69, 1.0, v69
	v_rcp_f32_e32 v86, v69
	v_mul_f32_e32 v69, 0xbfb8aa3b, v77
	v_exp_f32_e32 v69, v69
	s_nop 0
	v_add_f32_e32 v69, 1.0, v69
	v_rcp_f32_e32 v87, v69
	s_nop 0
	v_pk_mul_f32 v[76:77], v[76:77], v[86:87]
	s_nop 0
	v_cvt_pk_bf16_f32 v85, v76, v77
	v_and_b32_e32 v77, 0xffff0000, v99
	v_and_b32_e32 v76, 0xffff0000, v97
	v_pk_fma_f32 v[86:87], v[76:77], v[2:3], v[68:69] op_sel_hi:[1,0,0]
	v_pk_mov_b32 v[96:97], v[82:83], v[76:77] op_sel:[1,0]
	ds_write2_b64 v178, v[78:79], v[84:85] offset0:99 offset1:100
	v_pk_fma_f32 v[86:87], v[96:97], v[70:71], v[86:87] op_sel_hi:[1,0,1]
	v_and_b32_e32 v79, 0xffff0000, v101
	v_pk_fma_f32 v[82:83], v[82:83], v[72:73], v[86:87] op_sel_hi:[1,0,1]
	v_and_b32_e32 v85, 0xffff0000, v103
	v_pk_fma_f32 v[80:81], v[80:81], v[74:75], v[82:83] op_sel_hi:[1,0,1]
	v_mov_b32_e32 v84, v79
	v_mul_f32_e32 v69, 0xbfb8aa3b, v80
	v_exp_f32_e32 v69, v69
	v_mov_b32_e32 v78, v77
	v_and_b32_e32 v87, 0xffff0000, v95
	v_add_f32_e32 v69, 1.0, v69
	v_rcp_f32_e32 v82, v69
	v_mul_f32_e32 v69, 0xbfb8aa3b, v81
	v_exp_f32_e32 v69, v69
	s_nop 0
	v_add_f32_e32 v69, 1.0, v69
	v_rcp_f32_e32 v83, v69
	s_nop 0
	v_pk_mul_f32 v[80:81], v[80:81], v[82:83]
	v_pk_fma_f32 v[82:83], v[84:85], v[2:3], v[68:69] op_sel_hi:[1,0,0]
	v_cvt_pk_bf16_f32 v80, v80, v81
	v_pk_fma_f32 v[82:83], v[78:79], v[70:71], v[82:83] op_sel_hi:[1,0,1]
	s_nop 0
	v_pk_fma_f32 v[76:77], v[76:77], v[72:73], v[82:83] op_sel_hi:[1,0,1]
	s_nop 0
	v_pk_fma_f32 v[76:77], v[96:97], v[74:75], v[76:77] op_sel_hi:[1,0,1]
	s_nop 0
	v_mul_f32_e32 v69, 0xbfb8aa3b, v76
	v_exp_f32_e32 v69, v69
	s_nop 0
	v_add_f32_e32 v69, 1.0, v69
	v_rcp_f32_e32 v82, v69
	v_mul_f32_e32 v69, 0xbfb8aa3b, v77
	v_exp_f32_e32 v69, v69
	s_nop 0
	v_add_f32_e32 v69, 1.0, v69
	v_rcp_f32_e32 v83, v69
	s_nop 0
	v_pk_mul_f32 v[76:77], v[76:77], v[82:83]
	s_nop 0
	v_cvt_pk_bf16_f32 v81, v76, v77
	v_and_b32_e32 v77, 0xffff0000, v91
	v_and_b32_e32 v76, 0xffff0000, v89
	v_pk_fma_f32 v[88:89], v[76:77], v[2:3], v[68:69] op_sel_hi:[1,0,0]
	v_pk_mov_b32 v[90:91], v[84:85], v[76:77] op_sel:[1,0]
	v_and_b32_e32 v83, 0xffff0000, v93
	v_pk_fma_f32 v[88:89], v[90:91], v[70:71], v[88:89] op_sel_hi:[1,0,1]
	v_mov_b32_e32 v86, v83
	v_pk_fma_f32 v[84:85], v[84:85], v[72:73], v[88:89] op_sel_hi:[1,0,1]
	v_mov_b32_e32 v82, v77
	v_pk_fma_f32 v[78:79], v[78:79], v[74:75], v[84:85] op_sel_hi:[1,0,1]
	s_nop 0
	v_mul_f32_e32 v69, 0xbfb8aa3b, v78
	v_exp_f32_e32 v69, v69
	s_nop 0
	v_add_f32_e32 v69, 1.0, v69
	v_rcp_f32_e32 v84, v69
	v_mul_f32_e32 v69, 0xbfb8aa3b, v79
	v_exp_f32_e32 v69, v69
	s_nop 0
	v_add_f32_e32 v69, 1.0, v69
	v_rcp_f32_e32 v85, v69
	v_pk_fma_f32 v[68:69], v[86:87], v[2:3], v[68:69] op_sel_hi:[1,0,0]
	v_pk_mul_f32 v[78:79], v[78:79], v[84:85]
	v_pk_fma_f32 v[68:69], v[82:83], v[70:71], v[68:69] op_sel_hi:[1,0,1]
	v_cvt_pk_bf16_f32 v78, v78, v79
	v_pk_fma_f32 v[68:69], v[76:77], v[72:73], v[68:69] op_sel_hi:[1,0,1]
	s_nop 0
	v_pk_fma_f32 v[68:69], v[90:91], v[74:75], v[68:69] op_sel_hi:[1,0,1]
	s_nop 0
	v_mul_f32_e32 v2, 0xbfb8aa3b, v68
	v_exp_f32_e32 v2, v2
	s_nop 0
	v_add_f32_e32 v2, 1.0, v2
	v_rcp_f32_e32 v70, v2
	v_mul_f32_e32 v2, 0xbfb8aa3b, v69
	v_exp_f32_e32 v2, v2
	s_nop 0
	v_add_f32_e32 v2, 1.0, v2
	v_rcp_f32_e32 v71, v2
	s_nop 0
	v_pk_mul_f32 v[68:69], v[68:69], v[70:71]
	s_nop 0
	v_cvt_pk_bf16_f32 v79, v68, v69
	ds_write2_b64 v178, v[80:81], v[78:79] offset0:101 offset1:102
	s_waitcnt lgkmcnt(0)
	s_barrier
	global_load_dword v148, v3, s[10:11]
	s_lshl_b32 s10, s13, 6
	s_ashr_i32 s11, s10, 31
	s_lshl_b32 s13, s22, 4
	s_lshl_b64 s[10:11], s[10:11], 1
	s_add_i32 s13, s61, s13
	v_lshl_add_u64 v[150:151], v[144:145], 0, s[10:11]
	v_lshl_add_u64 v[152:153], v[146:147], 0, s[10:11]
	s_waitcnt vmcnt(0)
	v_mov_b32_e32 v149, v148
	s_branch .LBB0_572

.LBB0_584:
	v_mov_b32_e32 v208, 0
	v_mov_b32_e32 v209, 0
	v_mov_b32_e32 v210, 0
	v_mov_b32_e32 v211, 0
	v_mov_b32_e32 v6, 0
	v_mov_b32_e32 v158, 0
	v_mov_b32_e32 v154, 0
	v_mov_b32_e32 v150, 0
	v_mov_b32_e32 v106, 0
	v_mov_b32_e32 v7, 0
	s_and_b64 vcc, exec, s[50:51]
	v_mov_b32_e32 v105, 0
	s_cbranch_vccz .LBB0_569
	s_branch .LBB0_570

.LBB0_774:
	v_lshl_or_b32 v2, s8, 8, v107
	v_lshlrev_b64 v[20:21], 2, v[2:3]
	v_lshl_add_u64 v[4:5], s[90:91], 0, v[20:21]
	v_lshl_add_u64 v[8:9], s[62:63], 0, v[20:21]
	v_lshl_add_u64 v[12:13], s[72:73], 0, v[20:21]
	v_lshl_add_u64 v[16:17], s[74:75], 0, v[20:21]
	v_lshl_add_u64 v[20:21], s[78:79], 0, v[20:21]
	global_load_dwordx4 v[4:7], v[4:5], off
	s_nop 0
	global_load_dwordx4 v[8:11], v[8:9], off
	s_nop 0
	global_load_dwordx4 v[12:15], v[12:13], off
	s_nop 0
	global_load_dwordx4 v[16:19], v[16:17], off
	v_lshlrev_b32_e32 v2, 1, v2
	global_load_dwordx4 v[20:23], v[20:21], off
	v_lshl_add_u64 v[24:25], s[6:7], 0, v[2:3]
	v_cndmask_b32_e64 v2, 0, 1, s[2:3]
	v_cmp_ne_u32_e64 s[40:41], 1, v2
	s_andn2_b64 vcc, exec, s[2:3]
	v_mov_b32_e32 v40, 0
	s_cbranch_vccnz .LBB0_780
	v_add_co_u32_e32 v26, vcc, 0xffffc000, v24
	s_nop 1
	v_addc_co_u32_e32 v27, vcc, -1, v25, vcc
	global_load_dwordx2 v[210:211], v[26:27], off
	v_add_co_u32_e32 v26, vcc, 0xffffe000, v24
	s_nop 1
	v_addc_co_u32_e32 v27, vcc, -1, v25, vcc
	global_load_dwordx2 v[208:209], v[26:27], off offset:-1536
	s_and_b64 vcc, exec, s[40:41]
	v_mov_b32_e32 v41, 0
	s_cbranch_vccnz .LBB0_777

.LBB0_777:
	v_add_co_u32_e32 v26, vcc, 0x2000, v24
	s_nop 1
	v_addc_co_u32_e32 v27, vcc, 0, v25, vcc
	v_add_co_u32_e32 v28, vcc, 0x4000, v24
	s_nop 1
	v_addc_co_u32_e32 v29, vcc, 0, v25, vcc
	v_add_co_u32_e32 v30, vcc, 0x5000, v24
	s_lshl_b32 s12, s8, 2
	s_nop 0
	v_addc_co_u32_e32 v31, vcc, 0, v25, vcc
	global_load_dwordx2 v[94:95], v[24:25], off offset:3584
	global_load_dwordx2 v[92:93], v[26:27], off offset:2048
	global_load_dwordx2 v[88:89], v[28:29], off offset:512
	global_load_dwordx2 v[90:91], v[30:31], off offset:3072
	v_add_co_u32_e32 v26, vcc, 0x7000, v24
	s_nop 1
	v_addc_co_u32_e32 v27, vcc, 0, v25, vcc
	v_add_co_u32_e32 v28, vcc, 0x9000, v24
	v_or_b32_e32 v2, s12, v106
	s_nop 0
	v_addc_co_u32_e32 v29, vcc, 0, v25, vcc
	v_add_co_u32_e32 v30, vcc, s35, v24
	s_nop 1
	v_addc_co_u32_e32 v31, vcc, 0, v25, vcc
	v_add_co_u32_e32 v32, vcc, s36, v24
	v_lshl_add_u32 v2, v2, 9, s22
	s_nop 0
	v_addc_co_u32_e32 v33, vcc, 0, v25, vcc
	global_load_dwordx2 v[66:67], v[26:27], off offset:1536
	global_load_dwordx2 v[86:87], v[28:29], off
	global_load_dwordx2 v[62:63], v[30:31], off offset:2560
	global_load_dwordx2 v[64:65], v[32:33], off offset:1024
	v_add_co_u32_e32 v26, vcc, 0xd000, v24
	s_nop 1
	v_addc_co_u32_e32 v27, vcc, 0, v25, vcc
	v_add_co_u32_e32 v28, vcc, 0xf000, v24
	s_nop 1
	v_addc_co_u32_e32 v29, vcc, 0, v25, vcc
	v_add_co_u32_e32 v30, vcc, s56, v24
	s_mov_b32 s13, 0
	s_nop 0
	v_addc_co_u32_e32 v31, vcc, 0, v25, vcc
	v_add_co_u32_e32 v32, vcc, s33, v24
	s_waitcnt vmcnt(7)
	v_lshlrev_b32_e32 v104, 16, v210
	v_and_b32_e32 v100, 0xffff0000, v210
	v_lshlrev_b32_e32 v96, 16, v211
	v_and_b32_e32 v42, 0xffff0000, v211
	v_lshlrev_b32_e32 v118, 16, v208
	v_and_b32_e32 v102, 0xffff0000, v208
	v_lshlrev_b32_e32 v98, 16, v209
	v_and_b32_e32 v44, 0xffff0000, v209
	v_lshlrev_b32_e32 v122, 16, v40
	v_mov_b32_e32 v119, v122
	v_mov_b32_e32 v105, v118
	v_mov_b32_e32 v101, v102
	v_mov_b32_e32 v97, v98
	v_lshlrev_b32_e32 v120, 16, v94
	v_addc_co_u32_e32 v33, vcc, 0, v25, vcc
	global_load_dwordx2 v[58:59], v[26:27], off offset:3584
	global_load_dwordx2 v[60:61], v[28:29], off offset:2048
	global_load_dwordx2 v[54:55], v[30:31], off offset:512
	global_load_dwordx2 v[56:57], v[32:33], off offset:3072
	v_add_co_u32_e32 v26, vcc, s65, v24
	s_waitcnt vmcnt(10)
	v_lshlrev_b32_e32 v121, 16, v92
	v_addc_co_u32_e32 v27, vcc, 0, v25, vcc
	v_add_co_u32_e32 v28, vcc, s31, v24
	v_mov_b32_e32 v123, v120
	s_nop 0
	v_addc_co_u32_e32 v29, vcc, 0, v25, vcc
	v_add_co_u32_e32 v30, vcc, s58, v24
	v_pk_fma_f32 v[128:129], v[120:121], v[16:17], v[20:21] op_sel_hi:[1,0,0]
	s_nop 0
	v_addc_co_u32_e32 v31, vcc, 0, v25, vcc
	v_add_co_u32_e32 v24, vcc, s59, v24
	v_pk_fma_f32 v[128:129], v[122:123], v[12:13], v[128:129] op_sel_hi:[1,0,1]
	s_nop 0
	v_addc_co_u32_e32 v25, vcc, 0, v25, vcc
	global_load_dwordx2 v[50:51], v[26:27], off offset:1536
	global_load_dwordx2 v[52:53], v[28:29], off
	global_load_dwordx2 v[46:47], v[30:31], off offset:2560
	global_load_dwordx2 v[48:49], v[24:25], off offset:1024
	v_pk_fma_f32 v[128:129], v[118:119], v[8:9], v[128:129] op_sel_hi:[1,0,1]
	ds_read_b128 v[36:39], v2
	ds_read_b128 v[32:35], v2 offset:16
	ds_read_b128 v[28:31], v2 offset:32
	ds_read_b128 v[24:27], v2 offset:48
	v_pk_fma_f32 v[104:105], v[104:105], v[4:5], v[128:129] op_sel_hi:[1,0,1]
	s_waitcnt vmcnt(13)
	v_lshlrev_b32_e32 v125, 16, v88
	v_mul_f32_e32 v2, 0xbfb8aa3b, v104
	s_waitcnt vmcnt(12)
	v_lshlrev_b32_e32 v127, 16, v90
	v_exp_f32_e32 v2, v2
	v_mul_f32_e32 v43, 0xbfb8aa3b, v105
	v_mov_b32_e32 v126, v125
	v_mov_b32_e32 v124, v121
	v_exp_f32_e32 v43, v43
	v_pk_fma_f32 v[128:129], v[126:127], v[16:17], v[20:21] op_sel_hi:[1,0,0]
	v_add_f32_e32 v2, 1.0, v2
	v_pk_fma_f32 v[128:129], v[124:125], v[12:13], v[128:129] op_sel_hi:[1,0,1]
	v_rcp_f32_e32 v118, v2
	v_pk_fma_f32 v[120:121], v[120:121], v[8:9], v[128:129] op_sel_hi:[1,0,1]
	v_add_f32_e32 v2, 1.0, v43
	v_pk_fma_f32 v[120:121], v[122:123], v[4:5], v[120:121] op_sel_hi:[1,0,1]
	v_rcp_f32_e32 v119, v2
	v_mul_f32_e32 v43, 0xbfb8aa3b, v120
	v_exp_f32_e32 v43, v43
	v_mul_f32_e32 v45, 0xbfb8aa3b, v121
	v_exp_f32_e32 v45, v45
	v_pk_mul_f32 v[104:105], v[104:105], v[118:119]
	v_add_f32_e32 v2, 1.0, v43
	v_rcp_f32_e32 v122, v2
	v_add_f32_e32 v2, 1.0, v45
	v_rcp_f32_e32 v123, v2
	s_waitcnt lgkmcnt(3)
	v_pk_mul_f32 v[104:105], v[104:105], v[36:37]
	s_waitcnt vmcnt(8)
	v_lshlrev_b32_e32 v129, 16, v64
	v_cvt_pk_bf16_f32 v118, v104, v105
	v_pk_mul_f32 v[104:105], v[120:121], v[122:123]
	v_lshlrev_b32_e32 v123, 16, v62
	v_pk_mul_f32 v[104:105], v[104:105], v[38:39]
	v_mov_b32_e32 v128, v123
	v_cvt_pk_bf16_f32 v119, v104, v105
	v_lshlrev_b32_e32 v105, 16, v86
	v_lshlrev_b32_e32 v104, 16, v66
	v_pk_fma_f32 v[120:121], v[104:105], v[16:17], v[20:21] op_sel_hi:[1,0,0]
	v_pk_mov_b32 v[130:131], v[126:127], v[104:105] op_sel:[1,0]
	v_mov_b32_e32 v122, v105
	v_pk_fma_f32 v[120:121], v[130:131], v[12:13], v[120:121] op_sel_hi:[1,0,1]
	s_nop 0
	v_pk_fma_f32 v[120:121], v[126:127], v[8:9], v[120:121] op_sel_hi:[1,0,1]
	v_pk_fma_f32 v[126:127], v[128:129], v[16:17], v[20:21] op_sel_hi:[1,0,0]
	v_pk_fma_f32 v[120:121], v[124:125], v[4:5], v[120:121] op_sel_hi:[1,0,1]
	v_pk_fma_f32 v[126:127], v[122:123], v[12:13], v[126:127] op_sel_hi:[1,0,1]
	v_mul_f32_e32 v2, 0xbfb8aa3b, v120
	v_exp_f32_e32 v2, v2
	v_mul_f32_e32 v43, 0xbfb8aa3b, v121
	v_exp_f32_e32 v43, v43
	v_pk_fma_f32 v[104:105], v[104:105], v[8:9], v[126:127] op_sel_hi:[1,0,1]
	v_add_f32_e32 v2, 1.0, v2
	v_pk_fma_f32 v[104:105], v[130:131], v[4:5], v[104:105] op_sel_hi:[1,0,1]
	v_rcp_f32_e32 v124, v2
	v_add_f32_e32 v2, 1.0, v43
	v_mul_f32_e32 v43, 0xbfb8aa3b, v104
	v_exp_f32_e32 v43, v43
	v_mul_f32_e32 v45, 0xbfb8aa3b, v105
	v_exp_f32_e32 v45, v45
	v_rcp_f32_e32 v125, v2
	v_add_f32_e32 v2, 1.0, v43
	v_rcp_f32_e32 v126, v2
	v_add_f32_e32 v2, 1.0, v45
	v_rcp_f32_e32 v127, v2
	v_pk_mul_f32 v[120:121], v[120:121], v[124:125]
	s_waitcnt vmcnt(4)
	v_lshlrev_b32_e32 v125, 16, v56
	s_waitcnt lgkmcnt(2)
	v_pk_mul_f32 v[120:121], v[120:121], v[32:33]
	v_pk_mul_f32 v[104:105], v[104:105], v[126:127]
	v_cvt_pk_bf16_f32 v120, v120, v121
	v_pk_mul_f32 v[104:105], v[34:35], v[104:105]
	s_nop 0
	v_cvt_pk_bf16_f32 v121, v104, v105
	v_lshlrev_b32_e32 v105, 16, v60
	v_lshlrev_b32_e32 v104, 16, v58
	ds_write_b128 v116, v[118:121] offset:50176
	v_pk_fma_f32 v[118:119], v[104:105], v[16:17], v[20:21] op_sel_hi:[1,0,0]
	v_pk_mov_b32 v[126:127], v[128:129], v[104:105] op_sel:[1,0]
	v_lshlrev_b32_e32 v121, 16, v54
	v_pk_fma_f32 v[118:119], v[126:127], v[12:13], v[118:119] op_sel_hi:[1,0,1]
	v_mov_b32_e32 v124, v121
	v_pk_fma_f32 v[118:119], v[128:129], v[8:9], v[118:119] op_sel_hi:[1,0,1]
	v_mov_b32_e32 v120, v105
	v_pk_fma_f32 v[118:119], v[122:123], v[4:5], v[118:119] op_sel_hi:[1,0,1]
	v_pk_fma_f32 v[128:129], v[124:125], v[16:17], v[20:21] op_sel_hi:[1,0,0]
	v_mul_f32_e32 v2, 0xbfb8aa3b, v118
	v_exp_f32_e32 v2, v2
	v_mul_f32_e32 v43, 0xbfb8aa3b, v119
	v_exp_f32_e32 v43, v43
	v_pk_fma_f32 v[128:129], v[120:121], v[12:13], v[128:129] op_sel_hi:[1,0,1]
	v_add_f32_e32 v2, 1.0, v2
	v_pk_fma_f32 v[104:105], v[104:105], v[8:9], v[128:129] op_sel_hi:[1,0,1]
	v_rcp_f32_e32 v122, v2
	v_pk_fma_f32 v[104:105], v[126:127], v[4:5], v[104:105] op_sel_hi:[1,0,1]
	v_add_f32_e32 v2, 1.0, v43
	v_mul_f32_e32 v43, 0xbfb8aa3b, v104
	v_exp_f32_e32 v43, v43
	v_mul_f32_e32 v45, 0xbfb8aa3b, v105
	v_exp_f32_e32 v45, v45
	v_rcp_f32_e32 v123, v2
	v_add_f32_e32 v2, 1.0, v43
	v_rcp_f32_e32 v126, v2
	v_add_f32_e32 v2, 1.0, v45
	v_rcp_f32_e32 v127, v2
	v_pk_mul_f32 v[118:119], v[118:119], v[122:123]
	s_waitcnt vmcnt(1)
	v_lshlrev_b32_e32 v123, 16, v46
	s_waitcnt lgkmcnt(2)
	v_pk_mul_f32 v[118:119], v[28:29], v[118:119]
	v_pk_mul_f32 v[104:105], v[104:105], v[126:127]
	v_cvt_pk_bf16_f32 v118, v118, v119
	v_pk_mul_f32 v[104:105], v[30:31], v[104:105]
	s_waitcnt vmcnt(0)
	v_lshlrev_b32_e32 v127, 16, v48
	v_cvt_pk_bf16_f32 v119, v104, v105
	v_lshlrev_b32_e32 v104, 16, v50
	v_lshlrev_b32_e32 v105, 16, v52
	v_pk_fma_f32 v[128:129], v[104:105], v[16:17], v[20:21] op_sel_hi:[1,0,0]
	v_pk_mov_b32 v[130:131], v[124:125], v[104:105] op_sel:[1,0]
	v_mov_b32_e32 v126, v123
	v_pk_fma_f32 v[128:129], v[130:131], v[12:13], v[128:129] op_sel_hi:[1,0,1]
	v_mov_b32_e32 v122, v105
	v_pk_fma_f32 v[124:125], v[124:125], v[8:9], v[128:129] op_sel_hi:[1,0,1]
	v_pk_fma_f32 v[126:127], v[126:127], v[16:17], v[20:21] op_sel_hi:[1,0,0]
	v_pk_fma_f32 v[120:121], v[120:121], v[4:5], v[124:125] op_sel_hi:[1,0,1]
	v_pk_fma_f32 v[122:123], v[122:123], v[12:13], v[126:127] op_sel_hi:[1,0,1]
	v_mul_f32_e32 v2, 0xbfb8aa3b, v120
	v_exp_f32_e32 v2, v2
	v_mul_f32_e32 v43, 0xbfb8aa3b, v121
	v_exp_f32_e32 v43, v43
	v_pk_fma_f32 v[104:105], v[104:105], v[8:9], v[122:123] op_sel_hi:[1,0,1]
	v_add_f32_e32 v2, 1.0, v2
	v_pk_fma_f32 v[104:105], v[130:131], v[4:5], v[104:105] op_sel_hi:[1,0,1]
	v_rcp_f32_e32 v124, v2
	v_add_f32_e32 v2, 1.0, v43
	v_mul_f32_e32 v43, 0xbfb8aa3b, v104
	v_exp_f32_e32 v43, v43
	v_mul_f32_e32 v45, 0xbfb8aa3b, v105
	v_exp_f32_e32 v45, v45
	v_rcp_f32_e32 v125, v2
	v_add_f32_e32 v2, 1.0, v43
	v_rcp_f32_e32 v122, v2
	v_add_f32_e32 v2, 1.0, v45
	v_rcp_f32_e32 v123, v2
	v_pk_mul_f32 v[120:121], v[120:121], v[124:125]
	v_pk_mul_f32 v[104:105], v[104:105], v[122:123]
	s_waitcnt lgkmcnt(1)
	v_pk_mul_f32 v[120:121], v[24:25], v[120:121]
	v_pk_mul_f32 v[104:105], v[26:27], v[104:105]
	v_cvt_pk_bf16_f32 v120, v120, v121
	v_cvt_pk_bf16_f32 v121, v104, v105
	v_and_b32_e32 v105, 0xffff0000, v94
	ds_write_b128 v116, v[118:121] offset:50192
	v_and_b32_e32 v119, 0xffff0000, v92
	v_mov_b32_e32 v118, v105
	v_and_b32_e32 v104, 0xffff0000, v40
	v_pk_fma_f32 v[124:125], v[118:119], v[16:17], v[20:21] op_sel:[0,1,1]
	v_mov_b32_e32 v103, v104
	v_pk_fma_f32 v[124:125], v[104:105], v[12:13], v[124:125] op_sel:[0,1,0]
	v_and_b32_e32 v121, 0xffff0000, v88
	v_pk_fma_f32 v[124:125], v[102:103], v[8:9], v[124:125] op_sel:[0,1,0]
	v_and_b32_e32 v123, 0xffff0000, v90
	v_pk_fma_f32 v[100:101], v[100:101], v[4:5], v[124:125] op_sel:[0,1,0]
	v_mov_b32_e32 v122, v121
	v_mul_f32_e32 v2, 0xbfb8aa3b, v100
	v_exp_f32_e32 v2, v2
	v_mul_f32_e32 v40, 0xbfb8aa3b, v101
	v_mov_b32_e32 v120, v119
	v_exp_f32_e32 v40, v40
	v_pk_fma_f32 v[124:125], v[122:123], v[16:17], v[20:21] op_sel:[0,1,1]
	v_add_f32_e32 v2, 1.0, v2
	v_pk_fma_f32 v[124:125], v[120:121], v[12:13], v[124:125] op_sel:[0,1,0]
	v_rcp_f32_e32 v102, v2
	v_pk_fma_f32 v[118:119], v[118:119], v[8:9], v[124:125] op_sel:[0,1,0]
	v_add_f32_e32 v2, 1.0, v40
	v_pk_fma_f32 v[104:105], v[104:105], v[4:5], v[118:119] op_sel:[0,1,0]
	v_rcp_f32_e32 v103, v2
	v_mul_f32_e32 v40, 0xbfb8aa3b, v104
	v_exp_f32_e32 v40, v40
	v_mul_f32_e32 v43, 0xbfb8aa3b, v105
	v_exp_f32_e32 v43, v43
	v_pk_mul_f32 v[100:101], v[100:101], v[102:103]
	v_add_f32_e32 v2, 1.0, v40
	v_rcp_f32_e32 v118, v2
	v_add_f32_e32 v2, 1.0, v43
	v_rcp_f32_e32 v119, v2
	v_pk_mul_f32 v[100:101], v[100:101], v[36:37]
	v_add_u32_e32 v2, 0xc508, v116
	v_cvt_pk_bf16_f32 v100, v100, v101
	v_pk_mul_f32 v[102:103], v[104:105], v[118:119]
	v_and_b32_e32 v105, 0xffff0000, v62
	v_pk_mul_f32 v[102:103], v[102:103], v[38:39]
	v_and_b32_e32 v119, 0xffff0000, v64
	v_cvt_pk_bf16_f32 v101, v102, v103
	v_and_b32_e32 v103, 0xffff0000, v86
	v_and_b32_e32 v102, 0xffff0000, v66
	v_pk_fma_f32 v[124:125], v[102:103], v[16:17], v[20:21] op_sel:[0,1,1]
	v_pk_mov_b32 v[126:127], v[122:123], v[102:103] op_sel:[1,0]
	v_mov_b32_e32 v118, v105
	v_pk_fma_f32 v[124:125], v[126:127], v[12:13], v[124:125] op_sel:[0,1,0]
	v_mov_b32_e32 v104, v103
	v_pk_fma_f32 v[122:123], v[122:123], v[8:9], v[124:125] op_sel:[0,1,0]
	v_pk_fma_f32 v[124:125], v[118:119], v[16:17], v[20:21] op_sel:[0,1,1]
	v_pk_fma_f32 v[120:121], v[120:121], v[4:5], v[122:123] op_sel:[0,1,0]
	v_pk_fma_f32 v[124:125], v[104:105], v[12:13], v[124:125] op_sel:[0,1,0]
	v_mul_f32_e32 v40, 0xbfb8aa3b, v120
	v_exp_f32_e32 v40, v40
	v_mul_f32_e32 v43, 0xbfb8aa3b, v121
	v_exp_f32_e32 v43, v43
	v_pk_fma_f32 v[102:103], v[102:103], v[8:9], v[124:125] op_sel:[0,1,0]
	v_add_f32_e32 v40, 1.0, v40
	v_pk_fma_f32 v[102:103], v[126:127], v[4:5], v[102:103] op_sel:[0,1,0]
	v_rcp_f32_e32 v122, v40
	v_add_f32_e32 v40, 1.0, v43
	v_mul_f32_e32 v43, 0xbfb8aa3b, v102
	v_exp_f32_e32 v43, v43
	v_mul_f32_e32 v45, 0xbfb8aa3b, v103
	v_exp_f32_e32 v45, v45
	v_rcp_f32_e32 v123, v40
	v_add_f32_e32 v40, 1.0, v43
	v_rcp_f32_e32 v124, v40
	v_add_f32_e32 v40, 1.0, v45
	v_rcp_f32_e32 v125, v40
	v_pk_mul_f32 v[120:121], v[120:121], v[122:123]
	v_pk_mul_f32 v[102:103], v[102:103], v[124:125]
	v_pk_mul_f32 v[120:121], v[120:121], v[32:33]
	v_pk_mul_f32 v[102:103], v[34:35], v[102:103]
	v_cvt_pk_bf16_f32 v120, v120, v121
	v_cvt_pk_bf16_f32 v121, v102, v103
	ds_write2_b64 v2, v[100:101], v[120:121] offset1:1
	v_and_b32_e32 v101, 0xffff0000, v60
	v_and_b32_e32 v100, 0xffff0000, v58
	v_pk_fma_f32 v[122:123], v[100:101], v[16:17], v[20:21] op_sel:[0,1,1]
	v_pk_mov_b32 v[124:125], v[118:119], v[100:101] op_sel:[1,0]
	v_and_b32_e32 v103, 0xffff0000, v54
	v_pk_fma_f32 v[122:123], v[124:125], v[12:13], v[122:123] op_sel:[0,1,0]
	v_and_b32_e32 v121, 0xffff0000, v56
	v_pk_fma_f32 v[118:119], v[118:119], v[8:9], v[122:123] op_sel:[0,1,0]
	v_mov_b32_e32 v120, v103
	v_pk_fma_f32 v[104:105], v[104:105], v[4:5], v[118:119] op_sel:[0,1,0]
	v_mov_b32_e32 v102, v101
	v_mul_f32_e32 v2, 0xbfb8aa3b, v104
	v_exp_f32_e32 v2, v2
	v_mul_f32_e32 v40, 0xbfb8aa3b, v105
	v_exp_f32_e32 v40, v40
	v_pk_fma_f32 v[122:123], v[120:121], v[16:17], v[20:21] op_sel:[0,1,1]
	v_add_f32_e32 v2, 1.0, v2
	v_pk_fma_f32 v[122:123], v[102:103], v[12:13], v[122:123] op_sel:[0,1,0]
	v_rcp_f32_e32 v118, v2
	v_pk_fma_f32 v[100:101], v[100:101], v[8:9], v[122:123] op_sel:[0,1,0]
	v_add_f32_e32 v2, 1.0, v40
	v_pk_fma_f32 v[100:101], v[124:125], v[4:5], v[100:101] op_sel:[0,1,0]
	v_rcp_f32_e32 v119, v2
	v_mul_f32_e32 v40, 0xbfb8aa3b, v100
	v_exp_f32_e32 v40, v40
	v_mul_f32_e32 v43, 0xbfb8aa3b, v101
	v_exp_f32_e32 v43, v43
	v_pk_mul_f32 v[104:105], v[104:105], v[118:119]
	v_add_f32_e32 v2, 1.0, v40
	v_rcp_f32_e32 v122, v2
	v_add_f32_e32 v2, 1.0, v43
	v_rcp_f32_e32 v123, v2
	v_pk_mul_f32 v[104:105], v[28:29], v[104:105]
	v_and_b32_e32 v119, 0xffff0000, v46
	v_cvt_pk_bf16_f32 v104, v104, v105
	v_pk_mul_f32 v[100:101], v[100:101], v[122:123]
	v_and_b32_e32 v123, 0xffff0000, v48
	v_pk_mul_f32 v[100:101], v[30:31], v[100:101]
	v_mov_b32_e32 v122, v119
	v_cvt_pk_bf16_f32 v105, v100, v101
	v_and_b32_e32 v101, 0xffff0000, v52
	v_and_b32_e32 v100, 0xffff0000, v50
	v_pk_fma_f32 v[124:125], v[100:101], v[16:17], v[20:21] op_sel:[0,1,1]
	v_pk_mov_b32 v[126:127], v[120:121], v[100:101] op_sel:[1,0]
	v_mov_b32_e32 v118, v101
	v_pk_fma_f32 v[124:125], v[126:127], v[12:13], v[124:125] op_sel:[0,1,0]
	v_pk_fma_f32 v[16:17], v[122:123], v[16:17], v[20:21] op_sel:[0,1,1]
	v_pk_fma_f32 v[120:121], v[120:121], v[8:9], v[124:125] op_sel:[0,1,0]
	v_pk_fma_f32 v[12:13], v[118:119], v[12:13], v[16:17] op_sel:[0,1,0]
	v_pk_fma_f32 v[102:103], v[102:103], v[4:5], v[120:121] op_sel:[0,1,0]
	v_pk_fma_f32 v[8:9], v[100:101], v[8:9], v[12:13] op_sel:[0,1,0]
	v_mul_f32_e32 v40, 0xbfb8aa3b, v102
	v_pk_fma_f32 v[4:5], v[126:127], v[4:5], v[8:9] op_sel:[0,1,0]
	v_exp_f32_e32 v40, v40
	v_mul_f32_e32 v43, 0xbfb8aa3b, v103
	v_mul_f32_e32 v8, 0xbfb8aa3b, v4
	v_mul_f32_e32 v9, 0xbfb8aa3b, v5
	v_exp_f32_e32 v43, v43
	v_exp_f32_e32 v8, v8
	v_exp_f32_e32 v9, v9
	v_add_f32_e32 v40, 1.0, v40
	v_rcp_f32_e32 v120, v40
	v_add_f32_e32 v40, 1.0, v43
	v_add_f32_e32 v8, 1.0, v8
	v_add_f32_e32 v9, 1.0, v9
	v_rcp_f32_e32 v121, v40
	v_rcp_f32_e32 v8, v8
	v_rcp_f32_e32 v9, v9
	v_add_u32_e32 v2, 0xc518, v116
	v_pk_mul_f32 v[12:13], v[102:103], v[120:121]
	v_lshlrev_b32_e32 v17, 16, v91
	v_pk_mul_f32 v[4:5], v[4:5], v[8:9]
	v_pk_mul_f32 v[12:13], v[24:25], v[12:13]
	v_pk_mul_f32 v[4:5], v[26:27], v[4:5]
	v_cvt_pk_bf16_f32 v12, v12, v13
	v_cvt_pk_bf16_f32 v13, v4, v5
	v_lshlrev_b32_e32 v4, 16, v95
	v_lshlrev_b32_e32 v5, 16, v93
	v_lshlrev_b32_e32 v8, 16, v41
	v_mov_b32_e32 v9, v4
	v_pk_fma_f32 v[20:21], v[4:5], v[18:19], v[22:23] op_sel_hi:[1,0,0]
	v_mov_b32_e32 v99, v8
	v_pk_fma_f32 v[20:21], v[8:9], v[14:15], v[20:21] op_sel_hi:[1,0,1]
	ds_write2_b64 v2, v[104:105], v[12:13] offset1:1
	v_pk_fma_f32 v[20:21], v[98:99], v[10:11], v[20:21] op_sel_hi:[1,0,1]
	v_lshlrev_b32_e32 v13, 16, v89
	v_pk_fma_f32 v[20:21], v[96:97], v[6:7], v[20:21] op_sel_hi:[1,0,1]
	v_mov_b32_e32 v12, v5
	v_mul_f32_e32 v16, 0xbfb8aa3b, v21
	v_exp_f32_e32 v40, v16
	v_mov_b32_e32 v16, v13
	v_pk_fma_f32 v[98:99], v[16:17], v[18:19], v[22:23] op_sel_hi:[1,0,0]
	v_mul_f32_e32 v2, 0xbfb8aa3b, v20
	v_pk_fma_f32 v[98:99], v[12:13], v[14:15], v[98:99] op_sel_hi:[1,0,1]
	v_exp_f32_e32 v2, v2
	v_pk_fma_f32 v[4:5], v[4:5], v[10:11], v[98:99] op_sel_hi:[1,0,1]
	v_add_f32_e32 v2, 1.0, v2
	v_pk_fma_f32 v[4:5], v[8:9], v[6:7], v[4:5] op_sel_hi:[1,0,1]
	v_rcp_f32_e32 v96, v2
	v_mul_f32_e32 v8, 0xbfb8aa3b, v4
	v_exp_f32_e32 v8, v8
	v_mul_f32_e32 v9, 0xbfb8aa3b, v5
	v_exp_f32_e32 v9, v9
	v_add_f32_e32 v2, 1.0, v40
	v_rcp_f32_e32 v97, v2
	v_add_f32_e32 v2, 1.0, v8
	v_rcp_f32_e32 v8, v2
	v_add_f32_e32 v2, 1.0, v9
	v_rcp_f32_e32 v9, v2
	v_pk_mul_f32 v[20:21], v[20:21], v[96:97]
	v_pk_mul_f32 v[4:5], v[4:5], v[8:9]
	s_nop 0
	v_pk_mul_f32 v[4:5], v[4:5], v[38:39]
	v_pk_mul_f32 v[20:21], v[20:21], v[36:37]
	v_cvt_pk_bf16_f32 v97, v4, v5
	v_lshlrev_b32_e32 v5, 16, v87
	v_lshlrev_b32_e32 v4, 16, v67
	v_pk_fma_f32 v[98:99], v[4:5], v[18:19], v[22:23] op_sel_hi:[1,0,0]
	v_pk_mov_b32 v[100:101], v[16:17], v[4:5] op_sel:[1,0]
	v_lshlrev_b32_e32 v9, 16, v63
	v_pk_fma_f32 v[98:99], v[100:101], v[14:15], v[98:99] op_sel_hi:[1,0,1]
	v_cvt_pk_bf16_f32 v96, v20, v21
	v_pk_fma_f32 v[16:17], v[16:17], v[10:11], v[98:99] op_sel_hi:[1,0,1]
	v_lshlrev_b32_e32 v21, 16, v65
	v_pk_fma_f32 v[12:13], v[12:13], v[6:7], v[16:17] op_sel_hi:[1,0,1]
	v_mov_b32_e32 v20, v9
	v_mul_f32_e32 v2, 0xbfb8aa3b, v12
	v_exp_f32_e32 v2, v2
	v_mul_f32_e32 v16, 0xbfb8aa3b, v13
	v_mov_b32_e32 v8, v5
	v_exp_f32_e32 v17, v16
	v_pk_fma_f32 v[98:99], v[20:21], v[18:19], v[22:23] op_sel_hi:[1,0,0]
	v_add_f32_e32 v2, 1.0, v2
	v_pk_fma_f32 v[98:99], v[8:9], v[14:15], v[98:99] op_sel_hi:[1,0,1]
	v_rcp_f32_e32 v16, v2
	v_pk_fma_f32 v[4:5], v[4:5], v[10:11], v[98:99] op_sel_hi:[1,0,1]
	v_add_f32_e32 v2, 1.0, v17
	v_pk_fma_f32 v[4:5], v[100:101], v[6:7], v[4:5] op_sel_hi:[1,0,1]
	s_nop 0
	v_mul_f32_e32 v17, 0xbfb8aa3b, v4
	v_exp_f32_e32 v40, v17
	v_mul_f32_e32 v17, 0xbfb8aa3b, v5
	v_exp_f32_e32 v43, v17
	v_rcp_f32_e32 v17, v2
	v_add_f32_e32 v2, 1.0, v40
	v_rcp_f32_e32 v100, v2
	v_add_f32_e32 v2, 1.0, v43
	v_rcp_f32_e32 v101, v2
	v_pk_mul_f32 v[12:13], v[12:13], v[16:17]
	v_lshlrev_b32_e32 v17, 16, v57
	v_pk_mul_f32 v[12:13], v[12:13], v[32:33]
	v_pk_mul_f32 v[4:5], v[4:5], v[100:101]
	v_cvt_pk_bf16_f32 v98, v12, v13
	v_pk_mul_f32 v[4:5], v[34:35], v[4:5]
	v_lshlrev_b32_e32 v13, 16, v55
	v_cvt_pk_bf16_f32 v99, v4, v5
	v_lshlrev_b32_e32 v5, 16, v61
	v_lshlrev_b32_e32 v4, 16, v59
	ds_write_b128 v116, v[96:99] offset:50704
	v_pk_fma_f32 v[96:97], v[4:5], v[18:19], v[22:23] op_sel_hi:[1,0,0]
	v_pk_mov_b32 v[98:99], v[20:21], v[4:5] op_sel:[1,0]
	v_mov_b32_e32 v12, v5
	v_pk_fma_f32 v[96:97], v[98:99], v[14:15], v[96:97] op_sel_hi:[1,0,1]
	s_nop 0
	v_pk_fma_f32 v[20:21], v[20:21], v[10:11], v[96:97] op_sel_hi:[1,0,1]
	s_nop 0
	v_pk_fma_f32 v[8:9], v[8:9], v[6:7], v[20:21] op_sel_hi:[1,0,1]
	s_nop 0
	v_mul_f32_e32 v2, 0xbfb8aa3b, v8
	v_mul_f32_e32 v16, 0xbfb8aa3b, v9
	v_exp_f32_e32 v2, v2
	v_exp_f32_e32 v21, v16
	v_mov_b32_e32 v16, v13
	v_pk_fma_f32 v[96:97], v[16:17], v[18:19], v[22:23] op_sel_hi:[1,0,0]
	v_add_f32_e32 v2, 1.0, v2
	v_pk_fma_f32 v[96:97], v[12:13], v[14:15], v[96:97] op_sel_hi:[1,0,1]
	v_rcp_f32_e32 v20, v2
	v_pk_fma_f32 v[4:5], v[4:5], v[10:11], v[96:97] op_sel_hi:[1,0,1]
	v_add_f32_e32 v2, 1.0, v21
	v_pk_fma_f32 v[4:5], v[98:99], v[6:7], v[4:5] op_sel_hi:[1,0,1]
	s_nop 0
	v_mul_f32_e32 v21, 0xbfb8aa3b, v4
	v_exp_f32_e32 v40, v21
	v_mul_f32_e32 v21, 0xbfb8aa3b, v5
	v_exp_f32_e32 v43, v21
	v_rcp_f32_e32 v21, v2
	v_add_f32_e32 v2, 1.0, v40
	v_rcp_f32_e32 v98, v2
	v_add_f32_e32 v2, 1.0, v43
	v_rcp_f32_e32 v99, v2
	v_pk_mul_f32 v[8:9], v[8:9], v[20:21]
	v_lshlrev_b32_e32 v21, 16, v49
	v_pk_mul_f32 v[8:9], v[28:29], v[8:9]
	v_pk_mul_f32 v[4:5], v[4:5], v[98:99]
	v_cvt_pk_bf16_f32 v96, v8, v9
	v_pk_mul_f32 v[4:5], v[30:31], v[4:5]
	v_lshlrev_b32_e32 v9, 16, v47
	v_cvt_pk_bf16_f32 v97, v4, v5
	v_lshlrev_b32_e32 v4, 16, v51
	v_lshlrev_b32_e32 v5, 16, v53
	v_pk_fma_f32 v[98:99], v[4:5], v[18:19], v[22:23] op_sel_hi:[1,0,0]
	v_pk_mov_b32 v[100:101], v[16:17], v[4:5] op_sel:[1,0]
	v_mov_b32_e32 v20, v9
	v_pk_fma_f32 v[98:99], v[100:101], v[14:15], v[98:99] op_sel_hi:[1,0,1]
	v_mov_b32_e32 v8, v5
	v_pk_fma_f32 v[16:17], v[16:17], v[10:11], v[98:99] op_sel_hi:[1,0,1]
	v_pk_fma_f32 v[20:21], v[20:21], v[18:19], v[22:23] op_sel_hi:[1,0,0]
	v_pk_fma_f32 v[12:13], v[12:13], v[6:7], v[16:17] op_sel_hi:[1,0,1]
	v_pk_fma_f32 v[8:9], v[8:9], v[14:15], v[20:21] op_sel_hi:[1,0,1]
	v_mul_f32_e32 v2, 0xbfb8aa3b, v12
	v_pk_fma_f32 v[4:5], v[4:5], v[10:11], v[8:9] op_sel_hi:[1,0,1]
	v_exp_f32_e32 v2, v2
	v_mul_f32_e32 v16, 0xbfb8aa3b, v13
	v_pk_fma_f32 v[4:5], v[100:101], v[6:7], v[4:5] op_sel_hi:[1,0,1]
	v_exp_f32_e32 v17, v16
	v_mul_f32_e32 v6, 0xbfb8aa3b, v4
	v_exp_f32_e32 v6, v6
	v_mul_f32_e32 v8, 0xbfb8aa3b, v5
	v_exp_f32_e32 v9, v8
	v_add_f32_e32 v2, 1.0, v2
	v_rcp_f32_e32 v16, v2
	v_add_f32_e32 v2, 1.0, v17
	v_rcp_f32_e32 v17, v2
	v_add_f32_e32 v2, 1.0, v6
	v_rcp_f32_e32 v8, v2
	v_add_f32_e32 v2, 1.0, v9
	v_rcp_f32_e32 v9, v2
	v_mov_b32_e32 v2, v19
	v_mov_b32_e32 v6, v23
	v_mov_b32_e32 v10, v15
	v_pk_mul_f32 v[4:5], v[4:5], v[8:9]
	v_and_b32_e32 v9, 0xffff0000, v93
	v_pk_mul_f32 v[4:5], v[26:27], v[4:5]
	v_mov_b32_e32 v43, v44
	v_cvt_pk_bf16_f32 v99, v4, v5
	v_and_b32_e32 v5, 0xffff0000, v95
	v_mov_b32_e32 v8, v5
	v_and_b32_e32 v4, 0xffff0000, v41
	v_pk_fma_f32 v[18:19], v[8:9], v[2:3], v[6:7] op_sel_hi:[1,0,0]
	v_mov_b32_e32 v45, v4
	v_pk_fma_f32 v[14:15], v[4:5], v[10:11], v[18:19] op_sel_hi:[1,0,1]
	v_mov_b32_e32 v18, v11
	v_pk_fma_f32 v[14:15], v[44:45], v[18:19], v[14:15] op_sel_hi:[1,0,1]
	v_mov_b32_e32 v20, v7
	v_pk_fma_f32 v[14:15], v[42:43], v[20:21], v[14:15] op_sel_hi:[1,0,1]
	v_pk_mul_f32 v[12:13], v[12:13], v[16:17]
	v_mul_f32_e32 v7, 0xbfb8aa3b, v14
	v_exp_f32_e32 v7, v7
	v_mul_f32_e32 v11, 0xbfb8aa3b, v15
	v_exp_f32_e32 v11, v11
	v_pk_mul_f32 v[12:13], v[24:25], v[12:13]
	v_add_f32_e32 v7, 1.0, v7
	v_cvt_pk_bf16_f32 v98, v12, v13
	v_and_b32_e32 v13, 0xffff0000, v89
	v_and_b32_e32 v17, 0xffff0000, v91
	v_mov_b32_e32 v16, v13
	v_rcp_f32_e32 v22, v7
	v_add_f32_e32 v7, 1.0, v11
	v_mov_b32_e32 v12, v9
	v_pk_fma_f32 v[40:41], v[16:17], v[2:3], v[6:7] op_sel_hi:[1,0,0]
	v_rcp_f32_e32 v23, v7
	v_pk_fma_f32 v[40:41], v[12:13], v[10:11], v[40:41] op_sel_hi:[1,0,1]
	ds_write_b128 v116, v[96:99] offset:50720
	v_pk_fma_f32 v[8:9], v[8:9], v[18:19], v[40:41] op_sel_hi:[1,0,1]
	v_pk_mul_f32 v[14:15], v[14:15], v[22:23]
	v_pk_fma_f32 v[4:5], v[4:5], v[20:21], v[8:9] op_sel_hi:[1,0,1]
	v_pk_mul_f32 v[14:15], v[14:15], v[36:37]
	v_mul_f32_e32 v8, 0xbfb8aa3b, v4
	v_exp_f32_e32 v8, v8
	v_mul_f32_e32 v9, 0xbfb8aa3b, v5
	v_exp_f32_e32 v9, v9
	v_cvt_pk_bf16_f32 v14, v14, v15
	v_add_f32_e32 v7, 1.0, v8
	v_rcp_f32_e32 v8, v7
	v_add_f32_e32 v7, 1.0, v9
	v_rcp_f32_e32 v9, v7
	v_add_u32_e32 v7, 0xc718, v116
	v_and_b32_e32 v23, 0xffff0000, v65
	v_pk_mul_f32 v[4:5], v[4:5], v[8:9]
	s_nop 0
	v_pk_mul_f32 v[4:5], v[4:5], v[38:39]
	v_and_b32_e32 v9, 0xffff0000, v63
	v_cvt_pk_bf16_f32 v15, v4, v5
	v_and_b32_e32 v5, 0xffff0000, v87
	v_and_b32_e32 v4, 0xffff0000, v67
	v_pk_fma_f32 v[36:37], v[4:5], v[2:3], v[6:7] op_sel_hi:[1,0,0]
	v_pk_mov_b32 v[38:39], v[16:17], v[4:5] op_sel:[1,0]
	v_mov_b32_e32 v22, v9
	v_pk_fma_f32 v[36:37], v[38:39], v[10:11], v[36:37] op_sel_hi:[1,0,1]
	v_mov_b32_e32 v8, v5
	v_pk_fma_f32 v[16:17], v[16:17], v[18:19], v[36:37] op_sel_hi:[1,0,1]
	v_pk_fma_f32 v[36:37], v[22:23], v[2:3], v[6:7] op_sel_hi:[1,0,0]
	v_pk_fma_f32 v[12:13], v[12:13], v[20:21], v[16:17] op_sel_hi:[1,0,1]
	s_nop 0
	v_mul_f32_e32 v11, 0xbfb8aa3b, v12
	v_exp_f32_e32 v11, v11
	v_mul_f32_e32 v16, 0xbfb8aa3b, v13
	v_exp_f32_e32 v17, v16
	v_add_f32_e32 v11, 1.0, v11
	v_rcp_f32_e32 v16, v11
	v_add_f32_e32 v11, 1.0, v17
	v_pk_fma_f32 v[36:37], v[8:9], v[10:11], v[36:37] op_sel_hi:[1,0,1]
	s_nop 0
	v_pk_fma_f32 v[4:5], v[4:5], v[18:19], v[36:37] op_sel_hi:[1,0,1]
	s_nop 0
	v_pk_fma_f32 v[4:5], v[38:39], v[20:21], v[4:5] op_sel_hi:[1,0,1]
	s_nop 0
	v_mul_f32_e32 v17, 0xbfb8aa3b, v4
	v_exp_f32_e32 v19, v17
	v_mul_f32_e32 v17, 0xbfb8aa3b, v5
	v_exp_f32_e32 v21, v17
	v_rcp_f32_e32 v17, v11
	v_add_f32_e32 v11, 1.0, v19
	v_rcp_f32_e32 v36, v11
	v_add_f32_e32 v11, 1.0, v21
	v_rcp_f32_e32 v37, v11
	v_pk_mul_f32 v[12:13], v[12:13], v[16:17]
	v_pk_mul_f32 v[4:5], v[4:5], v[36:37]
	v_pk_mul_f32 v[12:13], v[12:13], v[32:33]
	v_pk_mul_f32 v[4:5], v[34:35], v[4:5]
	v_cvt_pk_bf16_f32 v12, v12, v13
	v_cvt_pk_bf16_f32 v13, v4, v5
	v_and_b32_e32 v5, 0xffff0000, v61
	v_and_b32_e32 v4, 0xffff0000, v59
	v_pk_fma_f32 v[16:17], v[4:5], v[2:3], v[6:7] op_sel_hi:[1,0,0]
	v_pk_mov_b32 v[32:33], v[22:23], v[4:5] op_sel:[1,0]
	ds_write2_b64 v7, v[14:15], v[12:13] offset1:1
	v_pk_fma_f32 v[16:17], v[32:33], v[10:11], v[16:17] op_sel_hi:[1,0,1]
	v_and_b32_e32 v13, 0xffff0000, v55
	v_pk_fma_f32 v[16:17], v[22:23], v[18:19], v[16:17] op_sel_hi:[1,0,1]
	v_and_b32_e32 v15, 0xffff0000, v57
	v_pk_fma_f32 v[8:9], v[8:9], v[20:21], v[16:17] op_sel_hi:[1,0,1]
	v_mov_b32_e32 v14, v13
	v_mul_f32_e32 v7, 0xbfb8aa3b, v8
	v_exp_f32_e32 v7, v7
	v_mul_f32_e32 v11, 0xbfb8aa3b, v9
	v_exp_f32_e32 v11, v11
	v_mov_b32_e32 v12, v5
	v_add_f32_e32 v7, 1.0, v7
	v_rcp_f32_e32 v16, v7
	v_add_f32_e32 v7, 1.0, v11
	v_pk_fma_f32 v[22:23], v[14:15], v[2:3], v[6:7] op_sel_hi:[1,0,0]
	s_nop 0
	v_pk_fma_f32 v[22:23], v[12:13], v[10:11], v[22:23] op_sel_hi:[1,0,1]
	s_nop 0
	v_pk_fma_f32 v[4:5], v[4:5], v[18:19], v[22:23] op_sel_hi:[1,0,1]
	s_nop 0
	v_pk_fma_f32 v[4:5], v[32:33], v[20:21], v[4:5] op_sel_hi:[1,0,1]
	s_nop 0
	v_mul_f32_e32 v11, 0xbfb8aa3b, v4
	v_exp_f32_e32 v11, v11
	v_mul_f32_e32 v17, 0xbfb8aa3b, v5
	v_exp_f32_e32 v19, v17
	v_rcp_f32_e32 v17, v7
	v_add_f32_e32 v7, 1.0, v11
	v_rcp_f32_e32 v22, v7
	v_add_f32_e32 v7, 1.0, v19
	v_rcp_f32_e32 v23, v7
	v_pk_mul_f32 v[8:9], v[8:9], v[16:17]
	v_add_u32_e32 v19, 0xc728, v116
	v_pk_mul_f32 v[8:9], v[28:29], v[8:9]
	v_pk_mul_f32 v[4:5], v[4:5], v[22:23]
	v_cvt_pk_bf16_f32 v8, v8, v9
	v_pk_mul_f32 v[4:5], v[30:31], v[4:5]
	v_and_b32_e32 v17, 0xffff0000, v47
	v_cvt_pk_bf16_f32 v9, v4, v5
	v_and_b32_e32 v5, 0xffff0000, v53
	v_and_b32_e32 v4, 0xffff0000, v51
	v_pk_fma_f32 v[28:29], v[4:5], v[2:3], v[6:7] op_sel_hi:[1,0,0]
	v_pk_mov_b32 v[30:31], v[14:15], v[4:5] op_sel:[1,0]
	v_and_b32_e32 v23, 0xffff0000, v49
	v_pk_fma_f32 v[28:29], v[30:31], v[10:11], v[28:29] op_sel_hi:[1,0,1]
	v_mov_b32_e32 v22, v17
	v_pk_fma_f32 v[14:15], v[14:15], v[18:19], v[28:29] op_sel_hi:[1,0,1]
	v_mov_b32_e32 v16, v5
	v_pk_fma_f32 v[12:13], v[12:13], v[20:21], v[14:15] op_sel_hi:[1,0,1]
	s_nop 0
	v_mul_f32_e32 v7, 0xbfb8aa3b, v12
	v_exp_f32_e32 v7, v7
	v_mul_f32_e32 v11, 0xbfb8aa3b, v13
	v_exp_f32_e32 v11, v11
	v_add_f32_e32 v7, 1.0, v7
	v_rcp_f32_e32 v14, v7
	v_add_f32_e32 v11, 1.0, v11
	v_pk_fma_f32 v[6:7], v[22:23], v[2:3], v[6:7] op_sel_hi:[1,0,0]
	v_rcp_f32_e32 v15, v11
	v_pk_fma_f32 v[6:7], v[16:17], v[10:11], v[6:7] op_sel_hi:[1,0,1]
	v_pk_mul_f32 v[10:11], v[12:13], v[14:15]
	v_pk_fma_f32 v[4:5], v[4:5], v[18:19], v[6:7] op_sel_hi:[1,0,1]
	v_pk_mul_f32 v[10:11], v[24:25], v[10:11]
	v_pk_fma_f32 v[4:5], v[30:31], v[20:21], v[4:5] op_sel_hi:[1,0,1]
	v_cvt_pk_bf16_f32 v10, v10, v11
	v_mul_f32_e32 v2, 0xbfb8aa3b, v4
	v_exp_f32_e32 v2, v2
	v_mul_f32_e32 v6, 0xbfb8aa3b, v5
	v_exp_f32_e32 v7, v6
	v_add_f32_e32 v2, 1.0, v2
	v_rcp_f32_e32 v6, v2
	v_add_f32_e32 v2, 1.0, v7
	v_rcp_f32_e32 v7, v2
	s_nop 0
	v_pk_mul_f32 v[4:5], v[4:5], v[6:7]
	s_nop 0
	v_pk_mul_f32 v[4:5], v[26:27], v[4:5]
	s_nop 0
	v_cvt_pk_bf16_f32 v11, v4, v5
	v_mov_b32_e32 v4, 0
	ds_write2_b64 v19, v[8:9], v[10:11] offset1:1
	v_mov_b32_e32 v5, v4
	v_mov_b32_e32 v6, v4
	v_mov_b32_e32 v7, v4
	v_mov_b32_e32 v8, v4
	v_mov_b32_e32 v9, v4
	v_mov_b32_e32 v10, v4
	v_mov_b32_e32 v11, v4
	v_mov_b32_e32 v12, v4
	v_mov_b32_e32 v13, v4
	v_mov_b32_e32 v14, v4
	v_mov_b32_e32 v15, v4
	v_mov_b32_e32 v16, v4
	v_mov_b32_e32 v17, v4
	v_mov_b32_e32 v18, v4
	v_mov_b32_e32 v19, v4
	v_mov_b32_e32 v24, v4
	v_mov_b32_e32 v25, v4
	v_mov_b32_e32 v26, v4
	v_mov_b32_e32 v27, v4
	v_mov_b32_e32 v32, v4
	v_mov_b32_e32 v33, v4
	v_mov_b32_e32 v34, v4
	v_mov_b32_e32 v35, v4
	v_mov_b32_e32 v36, v4
	v_mov_b32_e32 v37, v4
	v_mov_b32_e32 v38, v4
	v_mov_b32_e32 v39, v4
	v_mov_b32_e32 v40, v4
	v_mov_b32_e32 v41, v4
	v_mov_b32_e32 v42, v4
	v_mov_b32_e32 v43, v4
	v_mov_b32_e32 v44, v4
	v_mov_b32_e32 v45, v4
	v_mov_b32_e32 v46, v4
	v_mov_b32_e32 v47, v4
	v_mov_b32_e32 v48, v4
	v_mov_b32_e32 v49, v4
	v_mov_b32_e32 v50, v4
	v_mov_b32_e32 v51, v4
	v_mov_b32_e32 v52, v4
	v_mov_b32_e32 v53, v4
	v_mov_b32_e32 v54, v4
	v_mov_b32_e32 v55, v4
	v_mov_b32_e32 v56, v4
	v_mov_b32_e32 v57, v4
	v_mov_b32_e32 v58, v4
	v_mov_b32_e32 v59, v4
	v_mov_b32_e32 v60, v4
	v_mov_b32_e32 v61, v4
	v_mov_b32_e32 v62, v4
	v_mov_b32_e32 v63, v4
	v_mov_b32_e32 v64, v4
	v_mov_b32_e32 v65, v4
	v_mov_b32_e32 v66, v4
	v_mov_b32_e32 v67, v4
	v_mov_b32_e32 v28, v4
	v_mov_b32_e32 v29, v4
	v_mov_b32_e32 v30, v4
	v_mov_b32_e32 v31, v4
	v_mov_b32_e32 v20, v4
	v_mov_b32_e32 v21, v4
	v_mov_b32_e32 v22, v4
	v_mov_b32_e32 v23, v4
	s_waitcnt lgkmcnt(0)
	s_barrier

.LBB0_780:
	v_mov_b32_e32 v208, 0
	v_mov_b32_e32 v209, 0
	v_mov_b32_e32 v210, 0
	v_mov_b32_e32 v211, 0
	v_mov_b32_e32 v26, 0
	v_mov_b32_e32 v104, 0
	v_mov_b32_e32 v100, 0
	v_mov_b32_e32 v96, 0
	v_mov_b32_e32 v42, 0
	v_mov_b32_e32 v27, 0
	s_and_b64 vcc, exec, s[40:41]
	v_mov_b32_e32 v41, 0
	s_cbranch_vccz .LBB0_776
	s_branch .LBB0_777
